# v44 + s_setprio 1 for the loading wave during each K-loop load phase (prio 0 during its MFMA block)
# speedup vs baseline: 1.0031x; 1.0031x over previous
; #define PG8_STAGE(bufoff, gbase, voff) do { _Pragma("unroll") for (int _i = 0; _i < 2; ++_i) \
;         __builtin_amdgcn_global_load_lds((const unsigned*)((const char*)(gbase) + (voff)[_i]), (PG8_LAS unsigned*)(lds + (bufoff) + ldsw + _i * 8192), 16, 0, 0); } while (0)
; #define PG8_WAIT_V(n) asm volatile("s_waitcnt vmcnt(" #n ")" ::: "memory")
; #define PG8_WAIT_L(n) asm volatile("s_waitcnt lgkmcnt(" #n ")" ::: "memory")
; #define PG8_BAR __builtin_amdgcn_s_barrier()
; #define PG8_SCHED __builtin_amdgcn_sched_barrier(0)
;     ...
;             const bool last = (t == nt - 2);
;             const char* a1 = cA + (size_t)(t + 1) * kstep;
;             const char* a2 = last ? nA : cA + (size_t)(t + 2) * kstep; const char* b2 = last ? nB : cB + (size_t)(t + 2) * kstep;
;             const char* a3 = a2 + kstep; const char* b3 = b2 + kstep;
;             if (last && has_next) S.a_ready(nxt);
;             if (last) E.pre(pre, cur, wr, fr);
;             if constexpr (MIDK > 0) { if (t == MIDK / BK) E.mid(acc, cur, wr, wc, fr, fq); }
;             if constexpr (SP2) {
;             PG8_LDB(B0, 0, 0); PG8_LDB(B1, 0, 1); PG8_SCHED; PG8_LDA(At, 0, 0); PG8_STAGE(PG8_SA(1, 1), a1 + hstep, voffA);
;             PG8_WAIT_V(8); PG8_WAIT_L(0); PG8_BAR; PG8_MMA(0, 0, At, B0); PG8_MMA(0, 1, At, B1); PG8_BAR; PG8_SCHED;
;             PG8_LDA(At, 0, 1); PG8_STAGE(PG8_SB(0, 0), b2, voffB); PG8_STAGE(PG8_SB(0, 1), b2 + hstep, voffB); PG8_STAGE(PG8_SA(0, 0), a2, voffA);
;             PG8_WAIT_V(8); PG8_WAIT_L(0); PG8_BAR; PG8_MMA(1, 0, At, B0); PG8_MMA(1, 1, At, B1); PG8_BAR; PG8_SCHED;
.LBB0_248:
	v_add_u32_e32 v155, s68, v149
	ds_read_b128 v[166:169], v155
	ds_read_b128 v[170:173], v155 offset:1024
	ds_read_b128 v[174:177], v155 offset:2048
	ds_read_b128 v[178:181], v155 offset:3072
	v_add_u32_e32 v155, s69, v149
	ds_read_b128 v[182:185], v155
	ds_read_b128 v[186:189], v155 offset:1024
	ds_read_b128 v[190:193], v155 offset:2048
	ds_read_b128 v[194:197], v155 offset:3072
	s_add_u32 s33, s50, 0xfffc0080
	s_addc_u32 s54, s51, -1
	s_and_b64 s[52:53], s[52:53], exec
	s_cselect_b32 s55, s25, s54
	s_cselect_b32 s54, s34, s33
	s_cselect_b32 s53, s21, s73
	s_cselect_b32 s52, s35, s72
	v_lshl_add_u64 v[210:211], s[50:51], 0, v[138:139]
	s_add_i32 m0, s59, 0xc000
	ds_read_b128 v[198:201], v153
	ds_read_b128 v[202:205], v153 offset:1024
	ds_read_b128 v[206:209], v153 offset:2048
	ds_read_b128 v[214:217], v153 offset:3072
	ds_read_b128 v[218:221], v153 offset:4096
	ds_read_b128 v[222:225], v153 offset:5120
	ds_read_b128 v[226:229], v153 offset:6144
	ds_read_b128 v[230:233], v153 offset:7168
	global_load_lds_dwordx4 v[210:211], off
	s_add_i32 m0, s59, 0xe000
	v_lshl_add_u64 v[210:211], s[50:51], 0, v[140:141]
	global_load_lds_dwordx4 v[210:211], off
	s_waitcnt vmcnt(8) lgkmcnt(0)
	s_setprio 0
	s_barrier
	v_mfma_i32_16x16x64_i8 v[124:127], v[166:169], v[198:201], v[124:127]
	v_mfma_i32_16x16x64_i8 v[124:127], v[170:173], v[202:205], v[124:127]
	v_mfma_i32_16x16x64_i8 v[116:119], v[174:177], v[198:201], v[116:119]
	v_mfma_i32_16x16x64_i8 v[116:119], v[178:181], v[202:205], v[116:119]
	v_mfma_i32_16x16x64_i8 v[108:111], v[166:169], v[206:209], v[108:111]
	v_mfma_i32_16x16x64_i8 v[108:111], v[170:173], v[214:217], v[108:111]
	v_mfma_i32_16x16x64_i8 v[100:103], v[174:177], v[206:209], v[100:103]
	v_mfma_i32_16x16x64_i8 v[100:103], v[178:181], v[214:217], v[100:103]
	v_mfma_i32_16x16x64_i8 v[92:95], v[166:169], v[218:221], v[92:95]
	v_mfma_i32_16x16x64_i8 v[92:95], v[170:173], v[222:225], v[92:95]
	v_mfma_i32_16x16x64_i8 v[84:87], v[174:177], v[218:221], v[84:87]
	v_mfma_i32_16x16x64_i8 v[84:87], v[178:181], v[222:225], v[84:87]
	v_mfma_i32_16x16x64_i8 v[76:79], v[166:169], v[226:229], v[76:79]
	v_mfma_i32_16x16x64_i8 v[76:79], v[170:173], v[230:233], v[76:79]
	v_mfma_i32_16x16x64_i8 v[68:71], v[174:177], v[226:229], v[68:71]
	v_mfma_i32_16x16x64_i8 v[68:71], v[178:181], v[230:233], v[68:71]
	v_mfma_i32_16x16x64_i8 v[120:123], v[182:185], v[198:201], v[120:123]
	v_mfma_i32_16x16x64_i8 v[120:123], v[186:189], v[202:205], v[120:123]
	v_mfma_i32_16x16x64_i8 v[112:115], v[190:193], v[198:201], v[112:115]
	v_mfma_i32_16x16x64_i8 v[112:115], v[194:197], v[202:205], v[112:115]
	v_mfma_i32_16x16x64_i8 v[104:107], v[182:185], v[206:209], v[104:107]
	v_mfma_i32_16x16x64_i8 v[104:107], v[186:189], v[214:217], v[104:107]
	v_mfma_i32_16x16x64_i8 v[96:99], v[190:193], v[206:209], v[96:99]
	v_mfma_i32_16x16x64_i8 v[96:99], v[194:197], v[214:217], v[96:99]
	v_mfma_i32_16x16x64_i8 v[88:91], v[182:185], v[218:221], v[88:91]
	v_mfma_i32_16x16x64_i8 v[88:91], v[186:189], v[222:225], v[88:91]
	v_mfma_i32_16x16x64_i8 v[80:83], v[190:193], v[218:221], v[80:83]
	v_mfma_i32_16x16x64_i8 v[80:83], v[194:197], v[222:225], v[80:83]
	v_mfma_i32_16x16x64_i8 v[72:75], v[182:185], v[226:229], v[72:75]
	v_mfma_i32_16x16x64_i8 v[72:75], v[186:189], v[230:233], v[72:75]
	v_mfma_i32_16x16x64_i8 v[64:67], v[190:193], v[226:229], v[64:67]
	v_mfma_i32_16x16x64_i8 v[64:67], v[194:197], v[230:233], v[64:67]
	s_barrier
	s_setprio 1
	s_add_i32 s33, s68, s56
	v_lshl_add_u64 v[210:211], s[52:53], 0, v[132:133]
	s_mov_b32 m0, s33
	ds_read_b128 v[198:201], v153 offset:16384
	ds_read_b128 v[202:205], v153 offset:17408
	ds_read_b128 v[206:209], v153 offset:18432
	ds_read_b128 v[214:217], v153 offset:19456
	ds_read_b128 v[218:221], v153 offset:20480
	ds_read_b128 v[222:225], v153 offset:21504
	ds_read_b128 v[226:229], v153 offset:22528
	ds_read_b128 v[230:233], v153 offset:23552
	global_load_lds_dwordx4 v[210:211], off
	s_add_i32 m0, s33, 0x2000
	s_add_u32 s76, s52, 0x40000
	v_lshl_add_u64 v[234:235], s[52:53], 0, v[128:129]
	s_addc_u32 s77, s53, 0
	s_add_i32 s33, s69, s56
	global_load_lds_dwordx4 v[234:235], off
	v_lshl_add_u64 v[236:237], s[76:77], 0, v[132:133]
	s_mov_b32 m0, s33
	v_lshl_add_u64 v[238:239], s[54:55], 0, v[130:131]
	global_load_lds_dwordx4 v[236:237], off
	s_add_i32 m0, s33, 0x2000
	v_lshl_add_u64 v[236:237], s[76:77], 0, v[128:129]
	global_load_lds_dwordx4 v[236:237], off
	s_mov_b32 m0, s59
	v_lshl_add_u64 v[236:237], s[54:55], 0, v[134:135]
	global_load_lds_dwordx4 v[236:237], off
	s_mov_b32 m0, s60
	s_nop 0
	global_load_lds_dwordx4 v[238:239], off
	s_waitcnt vmcnt(8) lgkmcnt(0)
	s_setprio 0
	s_barrier
; #define PG8_STAGE(bufoff, gbase, voff) do { _Pragma("unroll") for (int _i = 0; _i < 2; ++_i) \
;         __builtin_amdgcn_global_load_lds((const unsigned*)((const char*)(gbase) + (voff)[_i]), (PG8_LAS unsigned*)(lds + (bufoff) + ldsw + _i * 8192), 16, 0, 0); } while (0)
; #define PG8_WAIT_V(n) asm volatile("s_waitcnt vmcnt(" #n ")" ::: "memory")
; #define PG8_WAIT_L(n) asm volatile("s_waitcnt lgkmcnt(" #n ")" ::: "memory")
; #define PG8_BAR __builtin_amdgcn_s_barrier()
; #define PG8_SCHED __builtin_amdgcn_sched_barrier(0)
;     ...
;             PG8_WAIT_V(8); PG8_WAIT_L(0); PG8_BAR; PG8_MMA(1, 0, At, B0); PG8_MMA(1, 1, At, B1); PG8_BAR; PG8_SCHED;
;             PG8_LDB(B0, 1, 0); PG8_LDB(B1, 1, 1); PG8_SCHED; PG8_LDA(At, 1, 0); PG8_STAGE(PG8_SA(0, 1), a2 + hstep, voffA);
;             PG8_WAIT_V(8); PG8_WAIT_L(0); PG8_BAR; PG8_MMA(0, 0, At, B0); PG8_MMA(0, 1, At, B1); PG8_BAR; PG8_SCHED;
	v_mfma_i32_16x16x64_i8 v[60:63], v[166:169], v[198:201], v[60:63]
	v_mfma_i32_16x16x64_i8 v[60:63], v[170:173], v[202:205], v[60:63]
	v_mfma_i32_16x16x64_i8 v[52:55], v[174:177], v[198:201], v[52:55]
	v_mfma_i32_16x16x64_i8 v[52:55], v[178:181], v[202:205], v[52:55]
	v_mfma_i32_16x16x64_i8 v[44:47], v[166:169], v[206:209], v[44:47]
	v_mfma_i32_16x16x64_i8 v[44:47], v[170:173], v[214:217], v[44:47]
	v_mfma_i32_16x16x64_i8 v[36:39], v[174:177], v[206:209], v[36:39]
	v_mfma_i32_16x16x64_i8 v[36:39], v[178:181], v[214:217], v[36:39]
	v_mfma_i32_16x16x64_i8 v[28:31], v[166:169], v[218:221], v[28:31]
	v_mfma_i32_16x16x64_i8 v[28:31], v[170:173], v[222:225], v[28:31]
	v_mfma_i32_16x16x64_i8 v[20:23], v[174:177], v[218:221], v[20:23]
	v_mfma_i32_16x16x64_i8 v[20:23], v[178:181], v[222:225], v[20:23]
	v_mfma_i32_16x16x64_i8 v[12:15], v[166:169], v[226:229], v[12:15]
	v_mfma_i32_16x16x64_i8 v[12:15], v[170:173], v[230:233], v[12:15]
	v_mfma_i32_16x16x64_i8 v[4:7], v[174:177], v[226:229], v[4:7]
	v_mfma_i32_16x16x64_i8 v[4:7], v[178:181], v[230:233], v[4:7]
	v_mfma_i32_16x16x64_i8 v[56:59], v[182:185], v[198:201], v[56:59]
	v_mfma_i32_16x16x64_i8 v[56:59], v[186:189], v[202:205], v[56:59]
	v_mfma_i32_16x16x64_i8 v[48:51], v[190:193], v[198:201], v[48:51]
	v_mfma_i32_16x16x64_i8 v[48:51], v[194:197], v[202:205], v[48:51]
	v_mfma_i32_16x16x64_i8 v[40:43], v[182:185], v[206:209], v[40:43]
	v_mfma_i32_16x16x64_i8 v[40:43], v[186:189], v[214:217], v[40:43]
	v_mfma_i32_16x16x64_i8 v[32:35], v[190:193], v[206:209], v[32:35]
	v_mfma_i32_16x16x64_i8 v[32:35], v[194:197], v[214:217], v[32:35]
	v_mfma_i32_16x16x64_i8 v[24:27], v[182:185], v[218:221], v[24:27]
	v_mfma_i32_16x16x64_i8 v[24:27], v[186:189], v[222:225], v[24:27]
	v_mfma_i32_16x16x64_i8 v[16:19], v[190:193], v[218:221], v[16:19]
	v_mfma_i32_16x16x64_i8 v[16:19], v[194:197], v[222:225], v[16:19]
	v_mfma_i32_16x16x64_i8 v[8:11], v[182:185], v[226:229], v[8:11]
	v_mfma_i32_16x16x64_i8 v[8:11], v[186:189], v[230:233], v[8:11]
	v_mfma_i32_16x16x64_i8 v[0:3], v[190:193], v[226:229], v[0:3]
	v_mfma_i32_16x16x64_i8 v[0:3], v[194:197], v[230:233], v[0:3]
	s_barrier
	s_setprio 1
	s_add_i32 s33, 0, 0x18000
	v_add_u32_e32 v155, s33, v149
	s_add_i32 s75, 0, 0x1c000
	ds_read_b128 v[166:169], v155
	ds_read_b128 v[170:173], v155 offset:1024
	ds_read_b128 v[174:177], v155 offset:2048
	ds_read_b128 v[178:181], v155 offset:3072
	v_add_u32_e32 v155, s75, v149
	ds_read_b128 v[182:185], v155
	ds_read_b128 v[186:189], v155 offset:1024
	ds_read_b128 v[190:193], v155 offset:2048
	ds_read_b128 v[194:197], v155 offset:3072
	s_add_u32 s54, s54, 0x40000
	s_addc_u32 s55, s55, 0
	s_mov_b32 m0, s61
	v_lshl_add_u64 v[240:241], s[54:55], 0, v[134:135]
	ds_read_b128 v[198:201], v153 offset:32768
	ds_read_b128 v[202:205], v153 offset:33792
	ds_read_b128 v[206:209], v153 offset:34816
	ds_read_b128 v[214:217], v153 offset:35840
	ds_read_b128 v[218:221], v153 offset:36864
	ds_read_b128 v[222:225], v153 offset:37888
	ds_read_b128 v[226:229], v153 offset:38912
	ds_read_b128 v[230:233], v153 offset:39936
	global_load_lds_dwordx4 v[240:241], off
	s_mov_b32 m0, s62
	v_lshl_add_u64 v[240:241], s[54:55], 0, v[130:131]
	global_load_lds_dwordx4 v[240:241], off
	s_waitcnt vmcnt(8) lgkmcnt(0)
	s_setprio 0
	s_barrier
	v_mfma_i32_16x16x64_i8 v[124:127], v[166:169], v[198:201], v[124:127]
	v_mfma_i32_16x16x64_i8 v[124:127], v[170:173], v[202:205], v[124:127]
	v_mfma_i32_16x16x64_i8 v[116:119], v[174:177], v[198:201], v[116:119]
	v_mfma_i32_16x16x64_i8 v[116:119], v[178:181], v[202:205], v[116:119]
	v_mfma_i32_16x16x64_i8 v[108:111], v[166:169], v[206:209], v[108:111]
	v_mfma_i32_16x16x64_i8 v[108:111], v[170:173], v[214:217], v[108:111]
	v_mfma_i32_16x16x64_i8 v[100:103], v[174:177], v[206:209], v[100:103]
	v_mfma_i32_16x16x64_i8 v[100:103], v[178:181], v[214:217], v[100:103]
	v_mfma_i32_16x16x64_i8 v[92:95], v[166:169], v[218:221], v[92:95]
	v_mfma_i32_16x16x64_i8 v[92:95], v[170:173], v[222:225], v[92:95]
	v_mfma_i32_16x16x64_i8 v[84:87], v[174:177], v[218:221], v[84:87]
	v_mfma_i32_16x16x64_i8 v[84:87], v[178:181], v[222:225], v[84:87]
	v_mfma_i32_16x16x64_i8 v[76:79], v[166:169], v[226:229], v[76:79]
	v_mfma_i32_16x16x64_i8 v[76:79], v[170:173], v[230:233], v[76:79]
	v_mfma_i32_16x16x64_i8 v[68:71], v[174:177], v[226:229], v[68:71]
	v_mfma_i32_16x16x64_i8 v[68:71], v[178:181], v[230:233], v[68:71]
	v_mfma_i32_16x16x64_i8 v[120:123], v[182:185], v[198:201], v[120:123]
	v_mfma_i32_16x16x64_i8 v[120:123], v[186:189], v[202:205], v[120:123]
	v_mfma_i32_16x16x64_i8 v[112:115], v[190:193], v[198:201], v[112:115]
	v_mfma_i32_16x16x64_i8 v[112:115], v[194:197], v[202:205], v[112:115]
	v_mfma_i32_16x16x64_i8 v[104:107], v[182:185], v[206:209], v[104:107]
	v_mfma_i32_16x16x64_i8 v[104:107], v[186:189], v[214:217], v[104:107]
	v_mfma_i32_16x16x64_i8 v[96:99], v[190:193], v[206:209], v[96:99]
	v_mfma_i32_16x16x64_i8 v[96:99], v[194:197], v[214:217], v[96:99]
	v_mfma_i32_16x16x64_i8 v[88:91], v[182:185], v[218:221], v[88:91]
	v_mfma_i32_16x16x64_i8 v[88:91], v[186:189], v[222:225], v[88:91]
	v_mfma_i32_16x16x64_i8 v[80:83], v[190:193], v[218:221], v[80:83]
	v_mfma_i32_16x16x64_i8 v[80:83], v[194:197], v[222:225], v[80:83]
	v_mfma_i32_16x16x64_i8 v[72:75], v[182:185], v[226:229], v[72:75]
	v_mfma_i32_16x16x64_i8 v[72:75], v[186:189], v[230:233], v[72:75]
	v_mfma_i32_16x16x64_i8 v[64:67], v[190:193], v[226:229], v[64:67]
	v_mfma_i32_16x16x64_i8 v[64:67], v[194:197], v[230:233], v[64:67]
	s_barrier
; #define PG8_STAGE(bufoff, gbase, voff) do { _Pragma("unroll") for (int _i = 0; _i < 2; ++_i) \
;         __builtin_amdgcn_global_load_lds((const unsigned*)((const char*)(gbase) + (voff)[_i]), (PG8_LAS unsigned*)(lds + (bufoff) + ldsw + _i * 8192), 16, 0, 0); } while (0)
; #define PG8_WAIT_V(n) asm volatile("s_waitcnt vmcnt(" #n ")" ::: "memory")
; #define PG8_WAIT_L(n) asm volatile("s_waitcnt lgkmcnt(" #n ")" ::: "memory")
; #define PG8_BAR __builtin_amdgcn_s_barrier()
; #define PG8_SCHED __builtin_amdgcn_sched_barrier(0)
;     ...
;             PG8_LDA(At, 1, 1); PG8_STAGE(PG8_SB(1, 0), b3, voffB); PG8_STAGE(PG8_SB(1, 1), b3 + hstep, voffB); PG8_STAGE(PG8_SA(1, 0), a3, voffA);
;             PG8_WAIT_V(8); PG8_WAIT_L(0); PG8_BAR; PG8_MMA(1, 0, At, B0); PG8_MMA(1, 1, At, B1); PG8_BAR; PG8_SCHED;
	s_setprio 1
	s_add_i32 s33, s33, s56
	v_lshl_add_u64 v[210:211], v[210:211], 0, s[10:11]
	s_mov_b32 m0, s33
	ds_read_b128 v[198:201], v153 offset:49152
	ds_read_b128 v[202:205], v153 offset:50176
	ds_read_b128 v[206:209], v153 offset:51200
	ds_read_b128 v[214:217], v153 offset:52224
	ds_read_b128 v[218:221], v153 offset:53248
	ds_read_b128 v[222:225], v153 offset:54272
	ds_read_b128 v[226:229], v153 offset:55296
	ds_read_b128 v[230:233], v153 offset:56320
	global_load_lds_dwordx4 v[210:211], off
	s_add_i32 m0, s33, 0x2000
	s_add_u32 s52, s52, 0x40080
	v_lshl_add_u64 v[210:211], v[234:235], 0, s[10:11]
	s_addc_u32 s53, s53, 0
	s_add_i32 s33, s75, s56
	global_load_lds_dwordx4 v[210:211], off
	s_mov_b32 m0, s33
	v_lshl_add_u64 v[210:211], s[52:53], 0, v[132:133]
	global_load_lds_dwordx4 v[210:211], off
	s_add_i32 m0, s33, 0x2000
	v_lshl_add_u64 v[210:211], s[52:53], 0, v[128:129]
	global_load_lds_dwordx4 v[210:211], off
	s_mov_b32 m0, s64
	v_lshl_add_u64 v[210:211], v[236:237], 0, s[10:11]
	global_load_lds_dwordx4 v[210:211], off
	s_mov_b32 m0, s65
	v_lshl_add_u64 v[210:211], v[238:239], 0, s[10:11]
	global_load_lds_dwordx4 v[210:211], off
	s_waitcnt vmcnt(8) lgkmcnt(0)
	s_setprio 0
	s_barrier
	v_mfma_i32_16x16x64_i8 v[60:63], v[166:169], v[198:201], v[60:63]
	v_mfma_i32_16x16x64_i8 v[60:63], v[170:173], v[202:205], v[60:63]
	v_mfma_i32_16x16x64_i8 v[52:55], v[174:177], v[198:201], v[52:55]
	v_mfma_i32_16x16x64_i8 v[52:55], v[178:181], v[202:205], v[52:55]
	v_mfma_i32_16x16x64_i8 v[44:47], v[166:169], v[206:209], v[44:47]
	v_mfma_i32_16x16x64_i8 v[44:47], v[170:173], v[214:217], v[44:47]
	v_mfma_i32_16x16x64_i8 v[36:39], v[174:177], v[206:209], v[36:39]
	v_mfma_i32_16x16x64_i8 v[36:39], v[178:181], v[214:217], v[36:39]
	v_mfma_i32_16x16x64_i8 v[28:31], v[166:169], v[218:221], v[28:31]
	v_mfma_i32_16x16x64_i8 v[28:31], v[170:173], v[222:225], v[28:31]
	v_mfma_i32_16x16x64_i8 v[20:23], v[174:177], v[218:221], v[20:23]
	v_mfma_i32_16x16x64_i8 v[20:23], v[178:181], v[222:225], v[20:23]
	v_mfma_i32_16x16x64_i8 v[12:15], v[166:169], v[226:229], v[12:15]
	v_mfma_i32_16x16x64_i8 v[12:15], v[170:173], v[230:233], v[12:15]
	v_mfma_i32_16x16x64_i8 v[4:7], v[174:177], v[226:229], v[4:7]
	v_mfma_i32_16x16x64_i8 v[4:7], v[178:181], v[230:233], v[4:7]
	v_mfma_i32_16x16x64_i8 v[56:59], v[182:185], v[198:201], v[56:59]
	v_mfma_i32_16x16x64_i8 v[56:59], v[186:189], v[202:205], v[56:59]
	v_mfma_i32_16x16x64_i8 v[48:51], v[190:193], v[198:201], v[48:51]
	v_mfma_i32_16x16x64_i8 v[48:51], v[194:197], v[202:205], v[48:51]
	v_mfma_i32_16x16x64_i8 v[40:43], v[182:185], v[206:209], v[40:43]
	v_mfma_i32_16x16x64_i8 v[40:43], v[186:189], v[214:217], v[40:43]
	v_mfma_i32_16x16x64_i8 v[32:35], v[190:193], v[206:209], v[32:35]
	v_mfma_i32_16x16x64_i8 v[32:35], v[194:197], v[214:217], v[32:35]
	v_mfma_i32_16x16x64_i8 v[24:27], v[182:185], v[218:221], v[24:27]
	v_mfma_i32_16x16x64_i8 v[24:27], v[186:189], v[222:225], v[24:27]
	v_mfma_i32_16x16x64_i8 v[16:19], v[190:193], v[218:221], v[16:19]
	v_mfma_i32_16x16x64_i8 v[16:19], v[194:197], v[222:225], v[16:19]
	v_mfma_i32_16x16x64_i8 v[8:11], v[182:185], v[226:229], v[8:11]
	v_mfma_i32_16x16x64_i8 v[8:11], v[186:189], v[230:233], v[8:11]
	v_mfma_i32_16x16x64_i8 v[0:3], v[190:193], v[226:229], v[0:3]
	v_mfma_i32_16x16x64_i8 v[0:3], v[194:197], v[230:233], v[0:3]
	s_barrier
	s_setprio 1
	s_add_i32 s74, s74, 2
	s_add_u32 s50, s50, 0x100
	s_addc_u32 s51, s51, 0
	s_add_u32 s72, s72, 0x100
	s_addc_u32 s73, s73, 0
	s_cmp_gt_u32 s74, 13
	s_cbranch_scc1 .LBB0_251

; #define PG8_STAGE(bufoff, gbase, voff) do { _Pragma("unroll") for (int _i = 0; _i < 2; ++_i) \
;         __builtin_amdgcn_global_load_lds((const unsigned*)((const char*)(gbase) + (voff)[_i]), (PG8_LAS unsigned*)(lds + (bufoff) + ldsw + _i * 8192), 16, 0, 0); } while (0)
; #define PG8_WAIT_V(n) asm volatile("s_waitcnt vmcnt(" #n ")" ::: "memory")
; #define PG8_WAIT_L(n) asm volatile("s_waitcnt lgkmcnt(" #n ")" ::: "memory")
; #define PG8_BAR __builtin_amdgcn_s_barrier()
; #define PG8_SCHED __builtin_amdgcn_sched_barrier(0)
;     ...
;             const bool last = (t == nt - 2);
;             const char* a1 = cA + (size_t)(t + 1) * kstep;
;             const char* a2 = last ? nA : cA + (size_t)(t + 2) * kstep; const char* b2 = last ? nB : cB + (size_t)(t + 2) * kstep;
;             const char* a3 = a2 + kstep; const char* b3 = b2 + kstep;
;             if (last && has_next) S.a_ready(nxt);
;             if (last) E.pre(pre, cur, wr, fr);
;             if constexpr (MIDK > 0) { if (t == MIDK / BK) E.mid(acc, cur, wr, wc, fr, fq); }
;             if constexpr (SP2) {
;             PG8_LDB(B0, 0, 0); PG8_LDB(B1, 0, 1); PG8_SCHED; PG8_LDA(At, 0, 0); PG8_STAGE(PG8_SA(1, 1), a1 + hstep, voffA);
;             PG8_WAIT_V(8); PG8_WAIT_L(0); PG8_BAR; PG8_MMA(0, 0, At, B0); PG8_MMA(0, 1, At, B1); PG8_BAR; PG8_SCHED;
;             PG8_LDA(At, 0, 1); PG8_STAGE(PG8_SB(0, 0), b2, voffB); PG8_STAGE(PG8_SB(0, 1), b2 + hstep, voffB); PG8_STAGE(PG8_SA(0, 0), a2, voffA);
;             PG8_WAIT_V(8); PG8_WAIT_L(0); PG8_BAR; PG8_MMA(1, 0, At, B0); PG8_MMA(1, 1, At, B1); PG8_BAR; PG8_SCHED;
.LBB0_335:
	ds_read_b128 v[128:131], v191
	ds_read_b128 v[132:135], v191 offset:1024
	ds_read_b128 v[136:139], v191 offset:2048
	ds_read_b128 v[140:143], v191 offset:3072
	ds_read_b128 v[144:147], v192
	ds_read_b128 v[148:151], v192 offset:1024
	ds_read_b128 v[168:171], v192 offset:2048
	ds_read_b128 v[172:175], v192 offset:3072
	s_add_u32 s33, s50, 0xffea0080
	s_addc_u32 s52, s51, -1
	s_cmpk_eq_i32 s72, 0x54
	s_cselect_b32 s55, s1, s52
	s_cselect_b32 s54, s0, s33
	s_cselect_b32 s53, s49, s35
	s_cselect_b32 s52, s48, s34
	v_lshl_add_u64 v[218:219], s[50:51], 0, v[160:161]
	s_add_i32 m0, s56, 0xc000
	ds_read_b128 v[176:179], v193
	ds_read_b128 v[180:183], v193 offset:1024
	ds_read_b128 v[184:187], v193 offset:2048
	ds_read_b128 v[196:199], v193 offset:3072
	ds_read_b128 v[200:203], v193 offset:4096
	ds_read_b128 v[204:207], v193 offset:5120
	ds_read_b128 v[208:211], v193 offset:6144
	ds_read_b128 v[214:217], v193 offset:7168
	global_load_lds_dwordx4 v[218:219], off
	s_add_i32 m0, s56, 0xe000
	v_lshl_add_u64 v[218:219], s[50:51], 0, v[162:163]
	global_load_lds_dwordx4 v[218:219], off
	s_waitcnt vmcnt(8) lgkmcnt(0)
	s_setprio 0
	s_barrier
	v_mfma_f32_16x16x32_bf16 v[124:127], v[128:131], v[176:179], v[124:127]
	v_mfma_f32_16x16x32_bf16 v[124:127], v[132:135], v[180:183], v[124:127]
	v_mfma_f32_16x16x32_bf16 v[120:123], v[136:139], v[176:179], v[120:123]
	v_mfma_f32_16x16x32_bf16 v[120:123], v[140:143], v[180:183], v[120:123]
	v_mfma_f32_16x16x32_bf16 v[108:111], v[128:131], v[184:187], v[108:111]
	v_mfma_f32_16x16x32_bf16 v[108:111], v[132:135], v[196:199], v[108:111]
	v_mfma_f32_16x16x32_bf16 v[104:107], v[136:139], v[184:187], v[104:107]
	v_mfma_f32_16x16x32_bf16 v[104:107], v[140:143], v[196:199], v[104:107]
	v_mfma_f32_16x16x32_bf16 v[92:95], v[128:131], v[200:203], v[92:95]
	v_mfma_f32_16x16x32_bf16 v[92:95], v[132:135], v[204:207], v[92:95]
	v_mfma_f32_16x16x32_bf16 v[88:91], v[136:139], v[200:203], v[88:91]
	v_mfma_f32_16x16x32_bf16 v[88:91], v[140:143], v[204:207], v[88:91]
	v_mfma_f32_16x16x32_bf16 v[76:79], v[128:131], v[208:211], v[76:79]
	v_mfma_f32_16x16x32_bf16 v[76:79], v[132:135], v[214:217], v[76:79]
	v_mfma_f32_16x16x32_bf16 v[72:75], v[136:139], v[208:211], v[72:75]
	v_mfma_f32_16x16x32_bf16 v[72:75], v[140:143], v[214:217], v[72:75]
	v_mfma_f32_16x16x32_bf16 v[116:119], v[144:147], v[176:179], v[116:119]
	v_mfma_f32_16x16x32_bf16 v[116:119], v[148:151], v[180:183], v[116:119]
	v_mfma_f32_16x16x32_bf16 v[112:115], v[168:171], v[176:179], v[112:115]
	v_mfma_f32_16x16x32_bf16 v[112:115], v[172:175], v[180:183], v[112:115]
	v_mfma_f32_16x16x32_bf16 v[100:103], v[144:147], v[184:187], v[100:103]
	v_mfma_f32_16x16x32_bf16 v[100:103], v[148:151], v[196:199], v[100:103]
	v_mfma_f32_16x16x32_bf16 v[96:99], v[168:171], v[184:187], v[96:99]
	v_mfma_f32_16x16x32_bf16 v[96:99], v[172:175], v[196:199], v[96:99]
	v_mfma_f32_16x16x32_bf16 v[84:87], v[144:147], v[200:203], v[84:87]
	v_mfma_f32_16x16x32_bf16 v[84:87], v[148:151], v[204:207], v[84:87]
	v_mfma_f32_16x16x32_bf16 v[80:83], v[168:171], v[200:203], v[80:83]
	v_mfma_f32_16x16x32_bf16 v[80:83], v[172:175], v[204:207], v[80:83]
	v_mfma_f32_16x16x32_bf16 v[68:71], v[144:147], v[208:211], v[68:71]
	v_mfma_f32_16x16x32_bf16 v[68:71], v[148:151], v[214:217], v[68:71]
	v_mfma_f32_16x16x32_bf16 v[64:67], v[168:171], v[208:211], v[64:67]
	v_mfma_f32_16x16x32_bf16 v[64:67], v[172:175], v[214:217], v[64:67]
	s_barrier
	s_setprio 1
	s_add_i32 s33, s66, s19
	v_lshl_add_u64 v[218:219], s[52:53], 0, v[154:155]
	s_mov_b32 m0, s33
	ds_read_b128 v[176:179], v193 offset:16384
	ds_read_b128 v[180:183], v193 offset:17408
	ds_read_b128 v[184:187], v193 offset:18432
	ds_read_b128 v[196:199], v193 offset:19456
	ds_read_b128 v[200:203], v193 offset:20480
	ds_read_b128 v[204:207], v193 offset:21504
	ds_read_b128 v[208:211], v193 offset:22528
	ds_read_b128 v[214:217], v193 offset:23552
	global_load_lds_dwordx4 v[218:219], off
	s_add_i32 m0, s33, 0x2000
	s_add_u32 s74, s52, 0x160000
	v_lshl_add_u64 v[220:221], s[52:53], 0, v[158:159]
	s_addc_u32 s75, s53, 0
	s_add_i32 s33, s67, s19
	global_load_lds_dwordx4 v[220:221], off
	v_lshl_add_u64 v[222:223], s[74:75], 0, v[154:155]
	s_mov_b32 m0, s33
	v_lshl_add_u64 v[224:225], s[54:55], 0, v[156:157]
	global_load_lds_dwordx4 v[222:223], off
	s_add_i32 m0, s33, 0x2000
	v_lshl_add_u64 v[222:223], s[74:75], 0, v[158:159]
	global_load_lds_dwordx4 v[222:223], off
	s_mov_b32 m0, s56
	v_lshl_add_u64 v[222:223], s[54:55], 0, v[152:153]
	global_load_lds_dwordx4 v[222:223], off
	s_mov_b32 m0, s57
	s_nop 0
	global_load_lds_dwordx4 v[224:225], off
	s_waitcnt vmcnt(8) lgkmcnt(0)
	s_setprio 0
	s_barrier
; #define PG8_STAGE(bufoff, gbase, voff) do { _Pragma("unroll") for (int _i = 0; _i < 2; ++_i) \
;         __builtin_amdgcn_global_load_lds((const unsigned*)((const char*)(gbase) + (voff)[_i]), (PG8_LAS unsigned*)(lds + (bufoff) + ldsw + _i * 8192), 16, 0, 0); } while (0)
; #define PG8_WAIT_V(n) asm volatile("s_waitcnt vmcnt(" #n ")" ::: "memory")
; #define PG8_WAIT_L(n) asm volatile("s_waitcnt lgkmcnt(" #n ")" ::: "memory")
; #define PG8_BAR __builtin_amdgcn_s_barrier()
; #define PG8_SCHED __builtin_amdgcn_sched_barrier(0)
;     ...
;             PG8_WAIT_V(8); PG8_WAIT_L(0); PG8_BAR; PG8_MMA(1, 0, At, B0); PG8_MMA(1, 1, At, B1); PG8_BAR; PG8_SCHED;
;             PG8_LDB(B0, 1, 0); PG8_LDB(B1, 1, 1); PG8_SCHED; PG8_LDA(At, 1, 0); PG8_STAGE(PG8_SA(0, 1), a2 + hstep, voffA);
;             PG8_WAIT_V(8); PG8_WAIT_L(0); PG8_BAR; PG8_MMA(0, 0, At, B0); PG8_MMA(0, 1, At, B1); PG8_BAR; PG8_SCHED;
	v_mfma_f32_16x16x32_bf16 v[60:63], v[128:131], v[176:179], v[60:63]
	v_mfma_f32_16x16x32_bf16 v[60:63], v[132:135], v[180:183], v[60:63]
	v_mfma_f32_16x16x32_bf16 v[56:59], v[136:139], v[176:179], v[56:59]
	v_mfma_f32_16x16x32_bf16 v[56:59], v[140:143], v[180:183], v[56:59]
	v_mfma_f32_16x16x32_bf16 v[44:47], v[128:131], v[184:187], v[44:47]
	v_mfma_f32_16x16x32_bf16 v[44:47], v[132:135], v[196:199], v[44:47]
	v_mfma_f32_16x16x32_bf16 v[40:43], v[136:139], v[184:187], v[40:43]
	v_mfma_f32_16x16x32_bf16 v[40:43], v[140:143], v[196:199], v[40:43]
	v_mfma_f32_16x16x32_bf16 v[28:31], v[128:131], v[200:203], v[28:31]
	v_mfma_f32_16x16x32_bf16 v[28:31], v[132:135], v[204:207], v[28:31]
	v_mfma_f32_16x16x32_bf16 v[24:27], v[136:139], v[200:203], v[24:27]
	v_mfma_f32_16x16x32_bf16 v[24:27], v[140:143], v[204:207], v[24:27]
	v_mfma_f32_16x16x32_bf16 v[12:15], v[128:131], v[208:211], v[12:15]
	v_mfma_f32_16x16x32_bf16 v[12:15], v[132:135], v[214:217], v[12:15]
	v_mfma_f32_16x16x32_bf16 v[8:11], v[136:139], v[208:211], v[8:11]
	v_mfma_f32_16x16x32_bf16 v[8:11], v[140:143], v[214:217], v[8:11]
	v_mfma_f32_16x16x32_bf16 v[52:55], v[144:147], v[176:179], v[52:55]
	v_mfma_f32_16x16x32_bf16 v[52:55], v[148:151], v[180:183], v[52:55]
	v_mfma_f32_16x16x32_bf16 v[48:51], v[168:171], v[176:179], v[48:51]
	v_mfma_f32_16x16x32_bf16 v[48:51], v[172:175], v[180:183], v[48:51]
	v_mfma_f32_16x16x32_bf16 v[36:39], v[144:147], v[184:187], v[36:39]
	v_mfma_f32_16x16x32_bf16 v[36:39], v[148:151], v[196:199], v[36:39]
	v_mfma_f32_16x16x32_bf16 v[32:35], v[168:171], v[184:187], v[32:35]
	v_mfma_f32_16x16x32_bf16 v[32:35], v[172:175], v[196:199], v[32:35]
	v_mfma_f32_16x16x32_bf16 v[20:23], v[144:147], v[200:203], v[20:23]
	v_mfma_f32_16x16x32_bf16 v[20:23], v[148:151], v[204:207], v[20:23]
	v_mfma_f32_16x16x32_bf16 v[16:19], v[168:171], v[200:203], v[16:19]
	v_mfma_f32_16x16x32_bf16 v[16:19], v[172:175], v[204:207], v[16:19]
	v_mfma_f32_16x16x32_bf16 v[4:7], v[144:147], v[208:211], v[4:7]
	v_mfma_f32_16x16x32_bf16 v[4:7], v[148:151], v[214:217], v[4:7]
	v_mfma_f32_16x16x32_bf16 v[0:3], v[168:171], v[208:211], v[0:3]
	v_mfma_f32_16x16x32_bf16 v[0:3], v[172:175], v[214:217], v[0:3]
	s_barrier
	s_setprio 1
	s_add_i32 s33, 0, 0x18000
	s_add_i32 s73, 0, 0x1c000
	v_add_u32_e32 v140, s33, v189
	v_add_u32_e32 v172, s73, v189
	ds_read_b128 v[128:131], v140
	ds_read_b128 v[132:135], v140 offset:1024
	ds_read_b128 v[136:139], v140 offset:2048
	ds_read_b128 v[140:143], v140 offset:3072
	ds_read_b128 v[144:147], v172
	ds_read_b128 v[148:151], v172 offset:1024
	ds_read_b128 v[168:171], v172 offset:2048
	ds_read_b128 v[172:175], v172 offset:3072
	s_add_u32 s54, s54, 0x160000
	s_addc_u32 s55, s55, 0
	s_mov_b32 m0, s58
	v_lshl_add_u64 v[226:227], s[54:55], 0, v[152:153]
	ds_read_b128 v[176:179], v193 offset:32768
	ds_read_b128 v[180:183], v193 offset:33792
	ds_read_b128 v[184:187], v193 offset:34816
	ds_read_b128 v[196:199], v193 offset:35840
	ds_read_b128 v[200:203], v193 offset:36864
	ds_read_b128 v[204:207], v193 offset:37888
	ds_read_b128 v[208:211], v193 offset:38912
	ds_read_b128 v[214:217], v193 offset:39936
	global_load_lds_dwordx4 v[226:227], off
	s_mov_b32 m0, s59
	v_lshl_add_u64 v[226:227], s[54:55], 0, v[156:157]
	global_load_lds_dwordx4 v[226:227], off
	s_waitcnt vmcnt(8) lgkmcnt(0)
	s_setprio 0
	s_barrier
	v_mfma_f32_16x16x32_bf16 v[124:127], v[128:131], v[176:179], v[124:127]
	v_mfma_f32_16x16x32_bf16 v[124:127], v[132:135], v[180:183], v[124:127]
	v_mfma_f32_16x16x32_bf16 v[120:123], v[136:139], v[176:179], v[120:123]
	v_mfma_f32_16x16x32_bf16 v[120:123], v[140:143], v[180:183], v[120:123]
	v_mfma_f32_16x16x32_bf16 v[108:111], v[128:131], v[184:187], v[108:111]
	v_mfma_f32_16x16x32_bf16 v[108:111], v[132:135], v[196:199], v[108:111]
	v_mfma_f32_16x16x32_bf16 v[104:107], v[136:139], v[184:187], v[104:107]
	v_mfma_f32_16x16x32_bf16 v[104:107], v[140:143], v[196:199], v[104:107]
	v_mfma_f32_16x16x32_bf16 v[92:95], v[128:131], v[200:203], v[92:95]
	v_mfma_f32_16x16x32_bf16 v[92:95], v[132:135], v[204:207], v[92:95]
	v_mfma_f32_16x16x32_bf16 v[88:91], v[136:139], v[200:203], v[88:91]
	v_mfma_f32_16x16x32_bf16 v[88:91], v[140:143], v[204:207], v[88:91]
	v_mfma_f32_16x16x32_bf16 v[76:79], v[128:131], v[208:211], v[76:79]
	v_mfma_f32_16x16x32_bf16 v[76:79], v[132:135], v[214:217], v[76:79]
	v_mfma_f32_16x16x32_bf16 v[72:75], v[136:139], v[208:211], v[72:75]
	v_mfma_f32_16x16x32_bf16 v[72:75], v[140:143], v[214:217], v[72:75]
	v_mfma_f32_16x16x32_bf16 v[116:119], v[144:147], v[176:179], v[116:119]
	v_mfma_f32_16x16x32_bf16 v[116:119], v[148:151], v[180:183], v[116:119]
	v_mfma_f32_16x16x32_bf16 v[112:115], v[168:171], v[176:179], v[112:115]
	v_mfma_f32_16x16x32_bf16 v[112:115], v[172:175], v[180:183], v[112:115]
	v_mfma_f32_16x16x32_bf16 v[100:103], v[144:147], v[184:187], v[100:103]
	v_mfma_f32_16x16x32_bf16 v[100:103], v[148:151], v[196:199], v[100:103]
	v_mfma_f32_16x16x32_bf16 v[96:99], v[168:171], v[184:187], v[96:99]
	v_mfma_f32_16x16x32_bf16 v[96:99], v[172:175], v[196:199], v[96:99]
	v_mfma_f32_16x16x32_bf16 v[84:87], v[144:147], v[200:203], v[84:87]
	v_mfma_f32_16x16x32_bf16 v[84:87], v[148:151], v[204:207], v[84:87]
	v_mfma_f32_16x16x32_bf16 v[80:83], v[168:171], v[200:203], v[80:83]
	v_mfma_f32_16x16x32_bf16 v[80:83], v[172:175], v[204:207], v[80:83]
	v_mfma_f32_16x16x32_bf16 v[68:71], v[144:147], v[208:211], v[68:71]
	v_mfma_f32_16x16x32_bf16 v[68:71], v[148:151], v[214:217], v[68:71]
	v_mfma_f32_16x16x32_bf16 v[64:67], v[168:171], v[208:211], v[64:67]
	v_mfma_f32_16x16x32_bf16 v[64:67], v[172:175], v[214:217], v[64:67]
	s_barrier
; #define PG8_STAGE(bufoff, gbase, voff) do { _Pragma("unroll") for (int _i = 0; _i < 2; ++_i) \
;         __builtin_amdgcn_global_load_lds((const unsigned*)((const char*)(gbase) + (voff)[_i]), (PG8_LAS unsigned*)(lds + (bufoff) + ldsw + _i * 8192), 16, 0, 0); } while (0)
; #define PG8_WAIT_V(n) asm volatile("s_waitcnt vmcnt(" #n ")" ::: "memory")
; #define PG8_WAIT_L(n) asm volatile("s_waitcnt lgkmcnt(" #n ")" ::: "memory")
; #define PG8_BAR __builtin_amdgcn_s_barrier()
; #define PG8_SCHED __builtin_amdgcn_sched_barrier(0)
;     ...
;             PG8_LDA(At, 1, 1); PG8_STAGE(PG8_SB(1, 0), b3, voffB); PG8_STAGE(PG8_SB(1, 1), b3 + hstep, voffB); PG8_STAGE(PG8_SA(1, 0), a3, voffA);
;             PG8_WAIT_V(8); PG8_WAIT_L(0); PG8_BAR; PG8_MMA(1, 0, At, B0); PG8_MMA(1, 1, At, B1); PG8_BAR; PG8_SCHED;
;     ...
;         if constexpr (ALIGN_EPI) { if (wr == 0) PG8_BAR; }
	s_setprio 1
	s_add_i32 s33, s33, s19
	v_lshl_add_u64 v[218:219], v[218:219], 0, s[24:25]
	s_mov_b32 m0, s33
	ds_read_b128 v[176:179], v193 offset:49152
	ds_read_b128 v[180:183], v193 offset:50176
	ds_read_b128 v[184:187], v193 offset:51200
	ds_read_b128 v[196:199], v193 offset:52224
	ds_read_b128 v[200:203], v193 offset:53248
	ds_read_b128 v[204:207], v193 offset:54272
	ds_read_b128 v[208:211], v193 offset:55296
	ds_read_b128 v[214:217], v193 offset:56320
	global_load_lds_dwordx4 v[218:219], off
	s_add_i32 m0, s33, 0x2000
	s_add_u32 s52, s52, 0x160080
	v_lshl_add_u64 v[218:219], v[220:221], 0, s[24:25]
	s_addc_u32 s53, s53, 0
	s_add_i32 s33, s73, s19
	global_load_lds_dwordx4 v[218:219], off
	s_mov_b32 m0, s33
	v_lshl_add_u64 v[218:219], s[52:53], 0, v[154:155]
	global_load_lds_dwordx4 v[218:219], off
	s_add_i32 m0, s33, 0x2000
	v_lshl_add_u64 v[218:219], s[52:53], 0, v[158:159]
	global_load_lds_dwordx4 v[218:219], off
	s_mov_b32 m0, s61
	v_lshl_add_u64 v[218:219], v[222:223], 0, s[24:25]
	global_load_lds_dwordx4 v[218:219], off
	s_mov_b32 m0, s62
	v_lshl_add_u64 v[218:219], v[224:225], 0, s[24:25]
	global_load_lds_dwordx4 v[218:219], off
	s_waitcnt vmcnt(8) lgkmcnt(0)
	s_setprio 0
	s_barrier
	v_mfma_f32_16x16x32_bf16 v[60:63], v[128:131], v[176:179], v[60:63]
	v_mfma_f32_16x16x32_bf16 v[60:63], v[132:135], v[180:183], v[60:63]
	v_mfma_f32_16x16x32_bf16 v[56:59], v[136:139], v[176:179], v[56:59]
	v_mfma_f32_16x16x32_bf16 v[56:59], v[140:143], v[180:183], v[56:59]
	v_mfma_f32_16x16x32_bf16 v[44:47], v[128:131], v[184:187], v[44:47]
	v_mfma_f32_16x16x32_bf16 v[44:47], v[132:135], v[196:199], v[44:47]
	v_mfma_f32_16x16x32_bf16 v[40:43], v[136:139], v[184:187], v[40:43]
	v_mfma_f32_16x16x32_bf16 v[40:43], v[140:143], v[196:199], v[40:43]
	v_mfma_f32_16x16x32_bf16 v[28:31], v[128:131], v[200:203], v[28:31]
	v_mfma_f32_16x16x32_bf16 v[28:31], v[132:135], v[204:207], v[28:31]
	v_mfma_f32_16x16x32_bf16 v[24:27], v[136:139], v[200:203], v[24:27]
	v_mfma_f32_16x16x32_bf16 v[24:27], v[140:143], v[204:207], v[24:27]
	v_mfma_f32_16x16x32_bf16 v[12:15], v[128:131], v[208:211], v[12:15]
	v_mfma_f32_16x16x32_bf16 v[12:15], v[132:135], v[214:217], v[12:15]
	v_mfma_f32_16x16x32_bf16 v[8:11], v[136:139], v[208:211], v[8:11]
	v_mfma_f32_16x16x32_bf16 v[8:11], v[140:143], v[214:217], v[8:11]
	v_mfma_f32_16x16x32_bf16 v[52:55], v[144:147], v[176:179], v[52:55]
	v_mfma_f32_16x16x32_bf16 v[52:55], v[148:151], v[180:183], v[52:55]
	v_mfma_f32_16x16x32_bf16 v[48:51], v[168:171], v[176:179], v[48:51]
	v_mfma_f32_16x16x32_bf16 v[48:51], v[172:175], v[180:183], v[48:51]
	v_mfma_f32_16x16x32_bf16 v[36:39], v[144:147], v[184:187], v[36:39]
	v_mfma_f32_16x16x32_bf16 v[36:39], v[148:151], v[196:199], v[36:39]
	v_mfma_f32_16x16x32_bf16 v[32:35], v[168:171], v[184:187], v[32:35]
	v_mfma_f32_16x16x32_bf16 v[32:35], v[172:175], v[196:199], v[32:35]
	v_mfma_f32_16x16x32_bf16 v[20:23], v[144:147], v[200:203], v[20:23]
	v_mfma_f32_16x16x32_bf16 v[20:23], v[148:151], v[204:207], v[20:23]
	v_mfma_f32_16x16x32_bf16 v[16:19], v[168:171], v[200:203], v[16:19]
	v_mfma_f32_16x16x32_bf16 v[16:19], v[172:175], v[204:207], v[16:19]
	v_mfma_f32_16x16x32_bf16 v[4:7], v[144:147], v[208:211], v[4:7]
	v_mfma_f32_16x16x32_bf16 v[4:7], v[148:151], v[214:217], v[4:7]
	v_mfma_f32_16x16x32_bf16 v[0:3], v[168:171], v[208:211], v[0:3]
	v_mfma_f32_16x16x32_bf16 v[0:3], v[172:175], v[214:217], v[0:3]
	s_barrier
	s_setprio 1
	s_add_i32 s72, s72, 2
	s_add_u32 s50, s50, 0x100
	s_addc_u32 s51, s51, 0
	s_add_u32 s34, s34, 0x100
	s_addc_u32 s35, s35, 0
	s_cmpk_gt_u32 s72, 0x55
	s_cbranch_scc0 .LBB0_335
	s_and_b64 vcc, exec, s[44:45]
	s_cbranch_vccz .LBB0_338
	s_barrier

; #define PG8_STAGE(bufoff, gbase, voff) do { _Pragma("unroll") for (int _i = 0; _i < 2; ++_i) \
;         __builtin_amdgcn_global_load_lds((const unsigned*)((const char*)(gbase) + (voff)[_i]), (PG8_LAS unsigned*)(lds + (bufoff) + ldsw + _i * 8192), 16, 0, 0); } while (0)
; #define PG8_WAIT_V(n) asm volatile("s_waitcnt vmcnt(" #n ")" ::: "memory")
; #define PG8_WAIT_L(n) asm volatile("s_waitcnt lgkmcnt(" #n ")" ::: "memory")
; #define PG8_BAR __builtin_amdgcn_s_barrier()
; #define PG8_SCHED __builtin_amdgcn_sched_barrier(0)
;     ...
;             const bool last = (t == nt - 2);
;             const char* a1 = cA + (size_t)(t + 1) * kstep;
;             const char* a2 = last ? nA : cA + (size_t)(t + 2) * kstep; const char* b2 = last ? nB : cB + (size_t)(t + 2) * kstep;
;             const char* a3 = a2 + kstep; const char* b3 = b2 + kstep;
;             if (last && has_next) S.a_ready(nxt);
;             if (last) E.pre(pre, cur, wr, fr);
;             if constexpr (MIDK > 0) { if (t == MIDK / BK) E.mid(acc, cur, wr, wc, fr, fq); }
;             if constexpr (SP2) {
;             PG8_LDB(B0, 0, 0); PG8_LDB(B1, 0, 1); PG8_SCHED; PG8_LDA(At, 0, 0); PG8_STAGE(PG8_SA(1, 1), a1 + hstep, voffA);
;             PG8_WAIT_V(8); PG8_WAIT_L(0); PG8_BAR; PG8_MMA(0, 0, At, B0); PG8_MMA(0, 1, At, B1); PG8_BAR; PG8_SCHED;
;             PG8_LDA(At, 0, 1); PG8_STAGE(PG8_SB(0, 0), b2, voffB); PG8_STAGE(PG8_SB(0, 1), b2 + hstep, voffB); PG8_STAGE(PG8_SA(0, 0), a2, voffA);
;             PG8_WAIT_V(8); PG8_WAIT_L(0); PG8_BAR; PG8_MMA(1, 0, At, B0); PG8_MMA(1, 1, At, B1); PG8_BAR; PG8_SCHED;
.LBB0_432:
	v_add_u32_e32 v142, s91, v205
	v_add_u32_e32 v146, s92, v205
	ds_read_b128 v[130:133], v142
	ds_read_b128 v[134:137], v142 offset:1024
	s_waitcnt lgkmcnt(0)
	ds_read_b128 v[138:141], v142 offset:2048
	ds_read_b128 v[142:145], v142 offset:3072
	ds_read_b128 v[188:191], v146
	ds_read_b128 v[192:195], v146 offset:1024
	ds_read_b128 v[196:199], v146 offset:2048
	ds_read_b128 v[200:203], v146 offset:3072
	s_add_u32 s33, s70, 0xfff80080
	s_addc_u32 s74, s71, -1
	s_and_b64 s[72:73], s[72:73], exec
	s_cselect_b32 s75, s18, s74
	s_cselect_b32 s74, s19, s33
	s_cselect_b32 s73, s34, s61
	s_cselect_b32 s72, s35, s10
	v_lshl_add_u64 v[146:147], s[70:71], 0, v[162:163]
	s_add_i32 m0, s69, 0xc000
	ds_read_b128 v[214:217], v159
	ds_read_b128 v[218:221], v159 offset:1024
	ds_read_b128 v[222:225], v159 offset:2048
	ds_read_b128 v[226:229], v159 offset:3072
	ds_read_b128 v[230:233], v159 offset:4096
	ds_read_b128 v[234:237], v159 offset:5120
	ds_read_b128 v[238:241], v159 offset:6144
	ds_read_b128 v[242:245], v159 offset:7168
	global_load_lds_dwordx4 v[146:147], off
	s_add_i32 m0, s69, 0xe000
	v_lshl_add_u64 v[146:147], s[70:71], 0, v[164:165]
	global_load_lds_dwordx4 v[146:147], off
	s_waitcnt vmcnt(8) lgkmcnt(0)
	s_setprio 0
	s_barrier
	v_mfma_f32_16x16x32_bf16 v[124:127], v[130:133], v[214:217], v[124:127]
	v_mfma_f32_16x16x32_bf16 v[124:127], v[134:137], v[218:221], v[124:127]
	v_mfma_f32_16x16x32_bf16 v[120:123], v[138:141], v[214:217], v[120:123]
	v_mfma_f32_16x16x32_bf16 v[120:123], v[142:145], v[218:221], v[120:123]
	v_mfma_f32_16x16x32_bf16 v[108:111], v[130:133], v[222:225], v[108:111]
	v_mfma_f32_16x16x32_bf16 v[108:111], v[134:137], v[226:229], v[108:111]
	v_mfma_f32_16x16x32_bf16 v[104:107], v[138:141], v[222:225], v[104:107]
	v_mfma_f32_16x16x32_bf16 v[104:107], v[142:145], v[226:229], v[104:107]
	v_mfma_f32_16x16x32_bf16 v[92:95], v[130:133], v[230:233], v[92:95]
	v_mfma_f32_16x16x32_bf16 v[92:95], v[134:137], v[234:237], v[92:95]
	v_mfma_f32_16x16x32_bf16 v[88:91], v[138:141], v[230:233], v[88:91]
	v_mfma_f32_16x16x32_bf16 v[88:91], v[142:145], v[234:237], v[88:91]
	v_mfma_f32_16x16x32_bf16 v[76:79], v[130:133], v[238:241], v[76:79]
	v_mfma_f32_16x16x32_bf16 v[76:79], v[134:137], v[242:245], v[76:79]
	v_mfma_f32_16x16x32_bf16 v[72:75], v[138:141], v[238:241], v[72:75]
	v_mfma_f32_16x16x32_bf16 v[72:75], v[142:145], v[242:245], v[72:75]
	v_mfma_f32_16x16x32_bf16 v[116:119], v[188:191], v[214:217], v[116:119]
	v_mfma_f32_16x16x32_bf16 v[116:119], v[192:195], v[218:221], v[116:119]
	v_mfma_f32_16x16x32_bf16 v[112:115], v[196:199], v[214:217], v[112:115]
	v_mfma_f32_16x16x32_bf16 v[112:115], v[200:203], v[218:221], v[112:115]
	v_mfma_f32_16x16x32_bf16 v[100:103], v[188:191], v[222:225], v[100:103]
	v_mfma_f32_16x16x32_bf16 v[100:103], v[192:195], v[226:229], v[100:103]
	v_mfma_f32_16x16x32_bf16 v[96:99], v[196:199], v[222:225], v[96:99]
	v_mfma_f32_16x16x32_bf16 v[96:99], v[200:203], v[226:229], v[96:99]
	v_mfma_f32_16x16x32_bf16 v[84:87], v[188:191], v[230:233], v[84:87]
	v_mfma_f32_16x16x32_bf16 v[84:87], v[192:195], v[234:237], v[84:87]
	v_mfma_f32_16x16x32_bf16 v[80:83], v[196:199], v[230:233], v[80:83]
	v_mfma_f32_16x16x32_bf16 v[80:83], v[200:203], v[234:237], v[80:83]
	v_mfma_f32_16x16x32_bf16 v[68:71], v[188:191], v[238:241], v[68:71]
	v_mfma_f32_16x16x32_bf16 v[68:71], v[192:195], v[242:245], v[68:71]
	v_mfma_f32_16x16x32_bf16 v[64:67], v[196:199], v[238:241], v[64:67]
	v_mfma_f32_16x16x32_bf16 v[64:67], v[200:203], v[242:245], v[64:67]
	s_barrier
	s_setprio 1
	s_add_i32 s33, s91, s82
	v_lshl_add_u64 v[146:147], s[72:73], 0, v[150:151]
	s_mov_b32 m0, s33
	ds_read_b128 v[214:217], v159 offset:16384
	ds_read_b128 v[218:221], v159 offset:17408
	ds_read_b128 v[222:225], v159 offset:18432
	ds_read_b128 v[226:229], v159 offset:19456
	ds_read_b128 v[230:233], v159 offset:20480
	ds_read_b128 v[234:237], v159 offset:21504
	ds_read_b128 v[238:241], v159 offset:22528
	ds_read_b128 v[242:245], v159 offset:23552
	global_load_lds_dwordx4 v[146:147], off
	s_add_i32 m0, s33, 0x2000
	s_add_u32 s94, s72, 0x80000
	v_lshl_add_u64 v[246:247], s[72:73], 0, v[154:155]
	s_addc_u32 s95, s73, 0
	s_add_i32 s33, s92, s82
	global_load_lds_dwordx4 v[246:247], off
	v_lshl_add_u64 v[248:249], s[94:95], 0, v[150:151]
	s_mov_b32 m0, s33
	v_lshl_add_u64 v[250:251], s[74:75], 0, v[152:153]
	global_load_lds_dwordx4 v[248:249], off
	s_add_i32 m0, s33, 0x2000
	v_lshl_add_u64 v[248:249], s[94:95], 0, v[154:155]
	global_load_lds_dwordx4 v[248:249], off
	s_mov_b32 m0, s69
	v_lshl_add_u64 v[248:249], s[74:75], 0, v[148:149]
	global_load_lds_dwordx4 v[248:249], off
	s_mov_b32 m0, s83
	s_nop 0
	global_load_lds_dwordx4 v[250:251], off
	s_waitcnt vmcnt(8) lgkmcnt(0)
	s_setprio 0
	s_barrier
; #define PG8_STAGE(bufoff, gbase, voff) do { _Pragma("unroll") for (int _i = 0; _i < 2; ++_i) \
;         __builtin_amdgcn_global_load_lds((const unsigned*)((const char*)(gbase) + (voff)[_i]), (PG8_LAS unsigned*)(lds + (bufoff) + ldsw + _i * 8192), 16, 0, 0); } while (0)
; #define PG8_WAIT_V(n) asm volatile("s_waitcnt vmcnt(" #n ")" ::: "memory")
; #define PG8_WAIT_L(n) asm volatile("s_waitcnt lgkmcnt(" #n ")" ::: "memory")
; #define PG8_BAR __builtin_amdgcn_s_barrier()
; #define PG8_SCHED __builtin_amdgcn_sched_barrier(0)
;     ...
;             PG8_WAIT_V(8); PG8_WAIT_L(0); PG8_BAR; PG8_MMA(1, 0, At, B0); PG8_MMA(1, 1, At, B1); PG8_BAR; PG8_SCHED;
;             PG8_LDB(B0, 1, 0); PG8_LDB(B1, 1, 1); PG8_SCHED; PG8_LDA(At, 1, 0); PG8_STAGE(PG8_SA(0, 1), a2 + hstep, voffA);
;             PG8_WAIT_V(8); PG8_WAIT_L(0); PG8_BAR; PG8_MMA(0, 0, At, B0); PG8_MMA(0, 1, At, B1); PG8_BAR; PG8_SCHED;
	v_mfma_f32_16x16x32_bf16 v[60:63], v[130:133], v[214:217], v[60:63]
	v_mfma_f32_16x16x32_bf16 v[60:63], v[134:137], v[218:221], v[60:63]
	v_mfma_f32_16x16x32_bf16 v[56:59], v[138:141], v[214:217], v[56:59]
	v_mfma_f32_16x16x32_bf16 v[56:59], v[142:145], v[218:221], v[56:59]
	v_mfma_f32_16x16x32_bf16 v[44:47], v[130:133], v[222:225], v[44:47]
	v_mfma_f32_16x16x32_bf16 v[44:47], v[134:137], v[226:229], v[44:47]
	v_mfma_f32_16x16x32_bf16 v[40:43], v[138:141], v[222:225], v[40:43]
	v_mfma_f32_16x16x32_bf16 v[40:43], v[142:145], v[226:229], v[40:43]
	v_mfma_f32_16x16x32_bf16 v[28:31], v[130:133], v[230:233], v[28:31]
	v_mfma_f32_16x16x32_bf16 v[28:31], v[134:137], v[234:237], v[28:31]
	v_mfma_f32_16x16x32_bf16 v[24:27], v[138:141], v[230:233], v[24:27]
	v_mfma_f32_16x16x32_bf16 v[24:27], v[142:145], v[234:237], v[24:27]
	v_mfma_f32_16x16x32_bf16 v[12:15], v[130:133], v[238:241], v[12:15]
	v_mfma_f32_16x16x32_bf16 v[12:15], v[134:137], v[242:245], v[12:15]
	v_mfma_f32_16x16x32_bf16 v[8:11], v[138:141], v[238:241], v[8:11]
	v_mfma_f32_16x16x32_bf16 v[8:11], v[142:145], v[242:245], v[8:11]
	v_mfma_f32_16x16x32_bf16 v[52:55], v[188:191], v[214:217], v[52:55]
	v_mfma_f32_16x16x32_bf16 v[52:55], v[192:195], v[218:221], v[52:55]
	v_mfma_f32_16x16x32_bf16 v[48:51], v[196:199], v[214:217], v[48:51]
	v_mfma_f32_16x16x32_bf16 v[48:51], v[200:203], v[218:221], v[48:51]
	v_mfma_f32_16x16x32_bf16 v[36:39], v[188:191], v[222:225], v[36:39]
	v_mfma_f32_16x16x32_bf16 v[36:39], v[192:195], v[226:229], v[36:39]
	v_mfma_f32_16x16x32_bf16 v[32:35], v[196:199], v[222:225], v[32:35]
	v_mfma_f32_16x16x32_bf16 v[32:35], v[200:203], v[226:229], v[32:35]
	v_mfma_f32_16x16x32_bf16 v[20:23], v[188:191], v[230:233], v[20:23]
	v_mfma_f32_16x16x32_bf16 v[20:23], v[192:195], v[234:237], v[20:23]
	v_mfma_f32_16x16x32_bf16 v[16:19], v[196:199], v[230:233], v[16:19]
	v_mfma_f32_16x16x32_bf16 v[16:19], v[200:203], v[234:237], v[16:19]
	v_mfma_f32_16x16x32_bf16 v[4:7], v[188:191], v[238:241], v[4:7]
	v_mfma_f32_16x16x32_bf16 v[4:7], v[192:195], v[242:245], v[4:7]
	v_mfma_f32_16x16x32_bf16 v[0:3], v[196:199], v[238:241], v[0:3]
	v_mfma_f32_16x16x32_bf16 v[0:3], v[200:203], v[242:245], v[0:3]
	s_barrier
	s_setprio 1
	s_add_i32 s33, 0, 0x18000
	s_add_i32 s94, 0, 0x1c000
	v_add_u32_e32 v142, s33, v205
	v_add_u32_e32 v156, s94, v205
	ds_read_b128 v[130:133], v142
	ds_read_b128 v[134:137], v142 offset:1024
	ds_read_b128 v[138:141], v142 offset:2048
	ds_read_b128 v[142:145], v142 offset:3072
	ds_read_b128 v[188:191], v156
	ds_read_b128 v[192:195], v156 offset:1024
	ds_read_b128 v[196:199], v156 offset:2048
	ds_read_b128 v[200:203], v156 offset:3072
	s_add_u32 s74, s74, 0x80000
	s_addc_u32 s75, s75, 0
	s_mov_b32 m0, s84
	v_lshl_add_u64 v[252:253], s[74:75], 0, v[148:149]
	ds_read_b128 v[214:217], v159 offset:32768
	ds_read_b128 v[218:221], v159 offset:33792
	ds_read_b128 v[222:225], v159 offset:34816
	ds_read_b128 v[226:229], v159 offset:35840
	ds_read_b128 v[230:233], v159 offset:36864
	ds_read_b128 v[234:237], v159 offset:37888
	ds_read_b128 v[238:241], v159 offset:38912
	ds_read_b128 v[242:245], v159 offset:39936
	global_load_lds_dwordx4 v[252:253], off
	s_mov_b32 m0, s85
	v_lshl_add_u64 v[252:253], s[74:75], 0, v[152:153]
	global_load_lds_dwordx4 v[252:253], off
	s_waitcnt vmcnt(8) lgkmcnt(0)
	s_setprio 0
	s_barrier
	v_mfma_f32_16x16x32_bf16 v[124:127], v[130:133], v[214:217], v[124:127]
	v_mfma_f32_16x16x32_bf16 v[124:127], v[134:137], v[218:221], v[124:127]
	v_mfma_f32_16x16x32_bf16 v[120:123], v[138:141], v[214:217], v[120:123]
	v_mfma_f32_16x16x32_bf16 v[120:123], v[142:145], v[218:221], v[120:123]
	v_mfma_f32_16x16x32_bf16 v[108:111], v[130:133], v[222:225], v[108:111]
	v_mfma_f32_16x16x32_bf16 v[108:111], v[134:137], v[226:229], v[108:111]
	v_mfma_f32_16x16x32_bf16 v[104:107], v[138:141], v[222:225], v[104:107]
	v_mfma_f32_16x16x32_bf16 v[104:107], v[142:145], v[226:229], v[104:107]
	v_mfma_f32_16x16x32_bf16 v[92:95], v[130:133], v[230:233], v[92:95]
	v_mfma_f32_16x16x32_bf16 v[92:95], v[134:137], v[234:237], v[92:95]
	v_mfma_f32_16x16x32_bf16 v[88:91], v[138:141], v[230:233], v[88:91]
	v_mfma_f32_16x16x32_bf16 v[88:91], v[142:145], v[234:237], v[88:91]
	v_mfma_f32_16x16x32_bf16 v[76:79], v[130:133], v[238:241], v[76:79]
	v_mfma_f32_16x16x32_bf16 v[76:79], v[134:137], v[242:245], v[76:79]
	v_mfma_f32_16x16x32_bf16 v[72:75], v[138:141], v[238:241], v[72:75]
	v_mfma_f32_16x16x32_bf16 v[72:75], v[142:145], v[242:245], v[72:75]
	v_mfma_f32_16x16x32_bf16 v[116:119], v[188:191], v[214:217], v[116:119]
	v_mfma_f32_16x16x32_bf16 v[116:119], v[192:195], v[218:221], v[116:119]
	v_mfma_f32_16x16x32_bf16 v[112:115], v[196:199], v[214:217], v[112:115]
	v_mfma_f32_16x16x32_bf16 v[112:115], v[200:203], v[218:221], v[112:115]
	v_mfma_f32_16x16x32_bf16 v[100:103], v[188:191], v[222:225], v[100:103]
	v_mfma_f32_16x16x32_bf16 v[100:103], v[192:195], v[226:229], v[100:103]
	v_mfma_f32_16x16x32_bf16 v[96:99], v[196:199], v[222:225], v[96:99]
	v_mfma_f32_16x16x32_bf16 v[96:99], v[200:203], v[226:229], v[96:99]
	v_mfma_f32_16x16x32_bf16 v[84:87], v[188:191], v[230:233], v[84:87]
	v_mfma_f32_16x16x32_bf16 v[84:87], v[192:195], v[234:237], v[84:87]
	v_mfma_f32_16x16x32_bf16 v[80:83], v[196:199], v[230:233], v[80:83]
	v_mfma_f32_16x16x32_bf16 v[80:83], v[200:203], v[234:237], v[80:83]
	v_mfma_f32_16x16x32_bf16 v[68:71], v[188:191], v[238:241], v[68:71]
	v_mfma_f32_16x16x32_bf16 v[68:71], v[192:195], v[242:245], v[68:71]
	v_mfma_f32_16x16x32_bf16 v[64:67], v[196:199], v[238:241], v[64:67]
	v_mfma_f32_16x16x32_bf16 v[64:67], v[200:203], v[242:245], v[64:67]
	s_barrier
; #define PG8_STAGE(bufoff, gbase, voff) do { _Pragma("unroll") for (int _i = 0; _i < 2; ++_i) \
;         __builtin_amdgcn_global_load_lds((const unsigned*)((const char*)(gbase) + (voff)[_i]), (PG8_LAS unsigned*)(lds + (bufoff) + ldsw + _i * 8192), 16, 0, 0); } while (0)
; #define PG8_WAIT_V(n) asm volatile("s_waitcnt vmcnt(" #n ")" ::: "memory")
; #define PG8_WAIT_L(n) asm volatile("s_waitcnt lgkmcnt(" #n ")" ::: "memory")
; #define PG8_BAR __builtin_amdgcn_s_barrier()
; #define PG8_SCHED __builtin_amdgcn_sched_barrier(0)
;     ...
;             PG8_LDA(At, 1, 1); PG8_STAGE(PG8_SB(1, 0), b3, voffB); PG8_STAGE(PG8_SB(1, 1), b3 + hstep, voffB); PG8_STAGE(PG8_SA(1, 0), a3, voffA);
;             PG8_WAIT_V(8); PG8_WAIT_L(0); PG8_BAR; PG8_MMA(1, 0, At, B0); PG8_MMA(1, 1, At, B1); PG8_BAR; PG8_SCHED;
	s_setprio 1
	s_add_i32 s33, s33, s82
	v_lshl_add_u64 v[146:147], v[146:147], 0, s[50:51]
	s_mov_b32 m0, s33
	ds_read_b128 v[214:217], v159 offset:49152
	ds_read_b128 v[218:221], v159 offset:50176
	ds_read_b128 v[222:225], v159 offset:51200
	ds_read_b128 v[226:229], v159 offset:52224
	ds_read_b128 v[230:233], v159 offset:53248
	ds_read_b128 v[234:237], v159 offset:54272
	ds_read_b128 v[238:241], v159 offset:55296
	ds_read_b128 v[242:245], v159 offset:56320
	global_load_lds_dwordx4 v[146:147], off
	s_add_i32 m0, s33, 0x2000
	s_add_u32 s72, s72, 0x80080
	v_lshl_add_u64 v[146:147], v[246:247], 0, s[50:51]
	s_addc_u32 s73, s73, 0
	s_add_i32 s33, s94, s82
	global_load_lds_dwordx4 v[146:147], off
	s_mov_b32 m0, s33
	v_lshl_add_u64 v[146:147], s[72:73], 0, v[150:151]
	global_load_lds_dwordx4 v[146:147], off
	s_add_i32 m0, s33, 0x2000
	v_lshl_add_u64 v[146:147], s[72:73], 0, v[154:155]
	global_load_lds_dwordx4 v[146:147], off
	s_mov_b32 m0, s86
	v_lshl_add_u64 v[146:147], v[248:249], 0, s[50:51]
	global_load_lds_dwordx4 v[146:147], off
	s_mov_b32 m0, s87
	v_lshl_add_u64 v[146:147], v[250:251], 0, s[50:51]
	global_load_lds_dwordx4 v[146:147], off
	s_waitcnt vmcnt(8) lgkmcnt(0)
	s_setprio 0
	s_barrier
	v_mfma_f32_16x16x32_bf16 v[60:63], v[130:133], v[214:217], v[60:63]
	v_mfma_f32_16x16x32_bf16 v[60:63], v[134:137], v[218:221], v[60:63]
	v_mfma_f32_16x16x32_bf16 v[56:59], v[138:141], v[214:217], v[56:59]
	v_mfma_f32_16x16x32_bf16 v[56:59], v[142:145], v[218:221], v[56:59]
	v_mfma_f32_16x16x32_bf16 v[44:47], v[130:133], v[222:225], v[44:47]
	v_mfma_f32_16x16x32_bf16 v[44:47], v[134:137], v[226:229], v[44:47]
	v_mfma_f32_16x16x32_bf16 v[40:43], v[138:141], v[222:225], v[40:43]
	v_mfma_f32_16x16x32_bf16 v[40:43], v[142:145], v[226:229], v[40:43]
	v_mfma_f32_16x16x32_bf16 v[28:31], v[130:133], v[230:233], v[28:31]
	v_mfma_f32_16x16x32_bf16 v[28:31], v[134:137], v[234:237], v[28:31]
	v_mfma_f32_16x16x32_bf16 v[24:27], v[138:141], v[230:233], v[24:27]
	v_mfma_f32_16x16x32_bf16 v[24:27], v[142:145], v[234:237], v[24:27]
	v_mfma_f32_16x16x32_bf16 v[12:15], v[130:133], v[238:241], v[12:15]
	v_mfma_f32_16x16x32_bf16 v[12:15], v[134:137], v[242:245], v[12:15]
	v_mfma_f32_16x16x32_bf16 v[8:11], v[138:141], v[238:241], v[8:11]
	v_mfma_f32_16x16x32_bf16 v[8:11], v[142:145], v[242:245], v[8:11]
	v_mfma_f32_16x16x32_bf16 v[52:55], v[188:191], v[214:217], v[52:55]
	v_mfma_f32_16x16x32_bf16 v[52:55], v[192:195], v[218:221], v[52:55]
	v_mfma_f32_16x16x32_bf16 v[48:51], v[196:199], v[214:217], v[48:51]
	v_mfma_f32_16x16x32_bf16 v[48:51], v[200:203], v[218:221], v[48:51]
	v_mfma_f32_16x16x32_bf16 v[36:39], v[188:191], v[222:225], v[36:39]
	v_mfma_f32_16x16x32_bf16 v[36:39], v[192:195], v[226:229], v[36:39]
	v_mfma_f32_16x16x32_bf16 v[32:35], v[196:199], v[222:225], v[32:35]
	v_mfma_f32_16x16x32_bf16 v[32:35], v[200:203], v[226:229], v[32:35]
	v_mfma_f32_16x16x32_bf16 v[20:23], v[188:191], v[230:233], v[20:23]
	v_mfma_f32_16x16x32_bf16 v[20:23], v[192:195], v[234:237], v[20:23]
	v_mfma_f32_16x16x32_bf16 v[16:19], v[196:199], v[230:233], v[16:19]
	v_mfma_f32_16x16x32_bf16 v[16:19], v[200:203], v[234:237], v[16:19]
	v_mfma_f32_16x16x32_bf16 v[4:7], v[188:191], v[238:241], v[4:7]
	v_mfma_f32_16x16x32_bf16 v[4:7], v[192:195], v[242:245], v[4:7]
	v_mfma_f32_16x16x32_bf16 v[0:3], v[196:199], v[238:241], v[0:3]
	v_mfma_f32_16x16x32_bf16 v[0:3], v[200:203], v[242:245], v[0:3]
	s_barrier
	s_setprio 1
	s_add_i32 s63, s63, 2
	s_add_u32 s70, s70, 0x100
	s_addc_u32 s71, s71, 0
	s_add_u32 s10, s10, 0x100
	s_addc_u32 s61, s61, 0
	s_cmp_gt_u32 s63, 29
	s_cbranch_scc1 .LBB0_435

; #define PG8_STAGE(bufoff, gbase, voff) do { _Pragma("unroll") for (int _i = 0; _i < 2; ++_i) \
;         __builtin_amdgcn_global_load_lds((const unsigned*)((const char*)(gbase) + (voff)[_i]), (PG8_LAS unsigned*)(lds + (bufoff) + ldsw + _i * 8192), 16, 0, 0); } while (0)
; #define PG8_WAIT_V(n) asm volatile("s_waitcnt vmcnt(" #n ")" ::: "memory")
; #define PG8_WAIT_L(n) asm volatile("s_waitcnt lgkmcnt(" #n ")" ::: "memory")
; #define PG8_BAR __builtin_amdgcn_s_barrier()
; #define PG8_SCHED __builtin_amdgcn_sched_barrier(0)
;     ...
;             const bool last = (t == nt - 2);
;             const char* a1 = cA + (size_t)(t + 1) * kstep;
;             const char* a2 = last ? nA : cA + (size_t)(t + 2) * kstep; const char* b2 = last ? nB : cB + (size_t)(t + 2) * kstep;
;             const char* a3 = a2 + kstep; const char* b3 = b2 + kstep;
;             if (last && has_next) S.a_ready(nxt);
;             if (last) E.pre(pre, cur, wr, fr);
;             if constexpr (MIDK > 0) { if (t == MIDK / BK) E.mid(acc, cur, wr, wc, fr, fq); }
;             if constexpr (SP2) {
;             PG8_LDB(B0, 0, 0); PG8_LDB(B1, 0, 1); PG8_SCHED; PG8_LDA(At, 0, 0); PG8_STAGE(PG8_SA(1, 1), a1 + hstep, voffA);
;             PG8_WAIT_V(8); PG8_WAIT_L(0); PG8_BAR; PG8_MMA(0, 0, At, B0); PG8_MMA(0, 1, At, B1); PG8_BAR; PG8_SCHED;
;             PG8_LDA(At, 0, 1); PG8_STAGE(PG8_SB(0, 0), b2, voffB); PG8_STAGE(PG8_SB(0, 1), b2 + hstep, voffB); PG8_STAGE(PG8_SA(0, 0), a2, voffA);
;             PG8_WAIT_V(8); PG8_WAIT_L(0); PG8_BAR; PG8_MMA(1, 0, At, B0); PG8_MMA(1, 1, At, B1); PG8_BAR; PG8_SCHED;
.LBB0_666:
	v_add_u32_e32 v1, s70, v175
	s_add_u32 s33, s52, s54
	ds_read_b128 v[140:143], v1
	ds_read_b128 v[144:147], v1 offset:1024
	ds_read_b128 v[148:151], v1 offset:2048
	ds_read_b128 v[152:155], v1 offset:3072
	v_add_u32_e32 v1, s71, v175
	s_addc_u32 s58, s53, s55
	ds_read_b128 v[190:193], v1
	ds_read_b128 v[194:197], v1 offset:1024
	ds_read_b128 v[198:201], v1 offset:2048
	ds_read_b128 v[202:205], v1 offset:3072
	s_add_u32 s33, s33, 0x100
	s_addc_u32 s76, s58, 0
	s_and_b64 s[58:59], s[56:57], exec
	s_cselect_b32 s59, s34, s76
	s_cselect_b32 s58, s35, s33
	s_add_u32 s33, s73, s54
	s_addc_u32 s76, s74, s55
	s_and_b64 s[56:57], s[56:57], exec
	s_cselect_b32 s57, s45, s76
	s_cselect_b32 s56, s47, s33
	v_lshl_add_u64 v[2:3], v[136:137], 0, s[54:55]
	s_add_i32 m0, s63, 0xc000
	ds_read_b128 v[206:209], v179
	ds_read_b128 v[214:217], v179 offset:1024
	ds_read_b128 v[218:221], v179 offset:2048
	ds_read_b128 v[222:225], v179 offset:3072
	ds_read_b128 v[226:229], v179 offset:4096
	ds_read_b128 v[230:233], v179 offset:5120
	ds_read_b128 v[234:237], v179 offset:6144
	ds_read_b128 v[238:241], v179 offset:7168
	global_load_lds_dwordx4 v[2:3], off
	s_add_i32 m0, s63, 0xe000
	v_lshl_add_u64 v[2:3], v[138:139], 0, s[54:55]
	global_load_lds_dwordx4 v[2:3], off
	s_waitcnt vmcnt(8) lgkmcnt(0)
	s_setprio 0
	s_barrier
	v_mfma_f32_16x16x32_bf16 v[128:131], v[140:143], v[206:209], v[128:131]
	v_mfma_f32_16x16x32_bf16 v[128:131], v[144:147], v[214:217], v[128:131]
	v_mfma_f32_16x16x32_bf16 v[124:127], v[148:151], v[206:209], v[124:127]
	v_mfma_f32_16x16x32_bf16 v[124:127], v[152:155], v[214:217], v[124:127]
	v_mfma_f32_16x16x32_bf16 v[112:115], v[140:143], v[218:221], v[112:115]
	v_mfma_f32_16x16x32_bf16 v[112:115], v[144:147], v[222:225], v[112:115]
	v_mfma_f32_16x16x32_bf16 v[108:111], v[148:151], v[218:221], v[108:111]
	v_mfma_f32_16x16x32_bf16 v[108:111], v[152:155], v[222:225], v[108:111]
	v_mfma_f32_16x16x32_bf16 v[96:99], v[140:143], v[226:229], v[96:99]
	v_mfma_f32_16x16x32_bf16 v[96:99], v[144:147], v[230:233], v[96:99]
	v_mfma_f32_16x16x32_bf16 v[92:95], v[148:151], v[226:229], v[92:95]
	v_mfma_f32_16x16x32_bf16 v[92:95], v[152:155], v[230:233], v[92:95]
	v_mfma_f32_16x16x32_bf16 v[80:83], v[140:143], v[234:237], v[80:83]
	v_mfma_f32_16x16x32_bf16 v[80:83], v[144:147], v[238:241], v[80:83]
	v_mfma_f32_16x16x32_bf16 v[76:79], v[148:151], v[234:237], v[76:79]
	v_mfma_f32_16x16x32_bf16 v[76:79], v[152:155], v[238:241], v[76:79]
	v_mfma_f32_16x16x32_bf16 v[120:123], v[190:193], v[206:209], v[120:123]
	v_mfma_f32_16x16x32_bf16 v[120:123], v[194:197], v[214:217], v[120:123]
	v_mfma_f32_16x16x32_bf16 v[116:119], v[198:201], v[206:209], v[116:119]
	v_mfma_f32_16x16x32_bf16 v[116:119], v[202:205], v[214:217], v[116:119]
	v_mfma_f32_16x16x32_bf16 v[104:107], v[190:193], v[218:221], v[104:107]
	v_mfma_f32_16x16x32_bf16 v[104:107], v[194:197], v[222:225], v[104:107]
	v_mfma_f32_16x16x32_bf16 v[100:103], v[198:201], v[218:221], v[100:103]
	v_mfma_f32_16x16x32_bf16 v[100:103], v[202:205], v[222:225], v[100:103]
	v_mfma_f32_16x16x32_bf16 v[88:91], v[190:193], v[226:229], v[88:91]
	v_mfma_f32_16x16x32_bf16 v[88:91], v[194:197], v[230:233], v[88:91]
	v_mfma_f32_16x16x32_bf16 v[84:87], v[198:201], v[226:229], v[84:87]
	v_mfma_f32_16x16x32_bf16 v[84:87], v[202:205], v[230:233], v[84:87]
	v_mfma_f32_16x16x32_bf16 v[72:75], v[190:193], v[234:237], v[72:75]
	v_mfma_f32_16x16x32_bf16 v[72:75], v[194:197], v[238:241], v[72:75]
	v_mfma_f32_16x16x32_bf16 v[68:71], v[198:201], v[234:237], v[68:71]
	v_mfma_f32_16x16x32_bf16 v[68:71], v[202:205], v[238:241], v[68:71]
	s_barrier
	s_setprio 1
	s_add_i32 s33, s70, s62
	v_lshl_add_u64 v[210:211], s[56:57], 0, v[158:159]
	s_mov_b32 m0, s33
	ds_read_b128 v[206:209], v179 offset:16384
	ds_read_b128 v[214:217], v179 offset:17408
	ds_read_b128 v[218:221], v179 offset:18432
	ds_read_b128 v[222:225], v179 offset:19456
	ds_read_b128 v[226:229], v179 offset:20480
	ds_read_b128 v[230:233], v179 offset:21504
	ds_read_b128 v[234:237], v179 offset:22528
	ds_read_b128 v[238:241], v179 offset:23552
	global_load_lds_dwordx4 v[210:211], off
	s_add_i32 m0, s33, 0x2000
	s_add_u32 s76, s56, 0x80000
	v_lshl_add_u64 v[242:243], s[56:57], 0, v[162:163]
	s_addc_u32 s77, s57, 0
	s_add_i32 s33, s71, s62
	global_load_lds_dwordx4 v[242:243], off
	v_lshl_add_u64 v[2:3], s[76:77], 0, v[158:159]
	s_mov_b32 m0, s33
	v_lshl_add_u64 v[244:245], s[58:59], 0, v[156:157]
	global_load_lds_dwordx4 v[2:3], off
	v_lshl_add_u64 v[2:3], s[76:77], 0, v[162:163]
	s_add_i32 m0, s33, 0x2000
	v_lshl_add_u64 v[246:247], s[58:59], 0, v[160:161]
	global_load_lds_dwordx4 v[2:3], off
	s_mov_b32 m0, s63
	s_nop 0
	global_load_lds_dwordx4 v[244:245], off
	s_mov_b32 m0, s64
	s_nop 0
	global_load_lds_dwordx4 v[246:247], off
	s_waitcnt vmcnt(8) lgkmcnt(0)
	s_setprio 0
	s_barrier
; #define PG8_STAGE(bufoff, gbase, voff) do { _Pragma("unroll") for (int _i = 0; _i < 2; ++_i) \
;         __builtin_amdgcn_global_load_lds((const unsigned*)((const char*)(gbase) + (voff)[_i]), (PG8_LAS unsigned*)(lds + (bufoff) + ldsw + _i * 8192), 16, 0, 0); } while (0)
; #define PG8_WAIT_V(n) asm volatile("s_waitcnt vmcnt(" #n ")" ::: "memory")
; #define PG8_WAIT_L(n) asm volatile("s_waitcnt lgkmcnt(" #n ")" ::: "memory")
; #define PG8_BAR __builtin_amdgcn_s_barrier()
; #define PG8_SCHED __builtin_amdgcn_sched_barrier(0)
;     ...
;             PG8_WAIT_V(8); PG8_WAIT_L(0); PG8_BAR; PG8_MMA(1, 0, At, B0); PG8_MMA(1, 1, At, B1); PG8_BAR; PG8_SCHED;
;             PG8_LDB(B0, 1, 0); PG8_LDB(B1, 1, 1); PG8_SCHED; PG8_LDA(At, 1, 0); PG8_STAGE(PG8_SA(0, 1), a2 + hstep, voffA);
;             PG8_WAIT_V(8); PG8_WAIT_L(0); PG8_BAR; PG8_MMA(0, 0, At, B0); PG8_MMA(0, 1, At, B1); PG8_BAR; PG8_SCHED;
	v_mfma_f32_16x16x32_bf16 v[64:67], v[140:143], v[206:209], v[64:67]
	v_mfma_f32_16x16x32_bf16 v[64:67], v[144:147], v[214:217], v[64:67]
	v_mfma_f32_16x16x32_bf16 v[60:63], v[148:151], v[206:209], v[60:63]
	v_mfma_f32_16x16x32_bf16 v[60:63], v[152:155], v[214:217], v[60:63]
	v_mfma_f32_16x16x32_bf16 v[48:51], v[140:143], v[218:221], v[48:51]
	v_mfma_f32_16x16x32_bf16 v[48:51], v[144:147], v[222:225], v[48:51]
	v_mfma_f32_16x16x32_bf16 v[44:47], v[148:151], v[218:221], v[44:47]
	v_mfma_f32_16x16x32_bf16 v[44:47], v[152:155], v[222:225], v[44:47]
	v_mfma_f32_16x16x32_bf16 v[32:35], v[140:143], v[226:229], v[32:35]
	v_mfma_f32_16x16x32_bf16 v[32:35], v[144:147], v[230:233], v[32:35]
	v_mfma_f32_16x16x32_bf16 v[28:31], v[148:151], v[226:229], v[28:31]
	v_mfma_f32_16x16x32_bf16 v[28:31], v[152:155], v[230:233], v[28:31]
	v_mfma_f32_16x16x32_bf16 v[16:19], v[140:143], v[234:237], v[16:19]
	v_mfma_f32_16x16x32_bf16 v[16:19], v[144:147], v[238:241], v[16:19]
	v_mfma_f32_16x16x32_bf16 v[12:15], v[148:151], v[234:237], v[12:15]
	v_mfma_f32_16x16x32_bf16 v[12:15], v[152:155], v[238:241], v[12:15]
	v_mfma_f32_16x16x32_bf16 v[56:59], v[190:193], v[206:209], v[56:59]
	v_mfma_f32_16x16x32_bf16 v[56:59], v[194:197], v[214:217], v[56:59]
	v_mfma_f32_16x16x32_bf16 v[52:55], v[198:201], v[206:209], v[52:55]
	v_mfma_f32_16x16x32_bf16 v[52:55], v[202:205], v[214:217], v[52:55]
	v_mfma_f32_16x16x32_bf16 v[40:43], v[190:193], v[218:221], v[40:43]
	v_mfma_f32_16x16x32_bf16 v[40:43], v[194:197], v[222:225], v[40:43]
	v_mfma_f32_16x16x32_bf16 v[36:39], v[198:201], v[218:221], v[36:39]
	v_mfma_f32_16x16x32_bf16 v[36:39], v[202:205], v[222:225], v[36:39]
	v_mfma_f32_16x16x32_bf16 v[24:27], v[190:193], v[226:229], v[24:27]
	v_mfma_f32_16x16x32_bf16 v[24:27], v[194:197], v[230:233], v[24:27]
	v_mfma_f32_16x16x32_bf16 v[20:23], v[198:201], v[226:229], v[20:23]
	v_mfma_f32_16x16x32_bf16 v[20:23], v[202:205], v[230:233], v[20:23]
	v_mfma_f32_16x16x32_bf16 v[8:11], v[190:193], v[234:237], v[8:11]
	v_mfma_f32_16x16x32_bf16 v[8:11], v[194:197], v[238:241], v[8:11]
	v_mfma_f32_16x16x32_bf16 v[2:5], v[198:201], v[234:237], v[4:7]
	v_mfma_f32_16x16x32_bf16 v[2:5], v[202:205], v[238:241], v[2:5]
	s_barrier
	s_setprio 1
	s_add_i32 s33, 0, 0x18000
	v_add_u32_e32 v1, s33, v175
	s_add_i32 s76, 0, 0x1c000
	ds_read_b128 v[140:143], v1
	ds_read_b128 v[144:147], v1 offset:1024
	ds_read_b128 v[148:151], v1 offset:2048
	ds_read_b128 v[152:155], v1 offset:3072
	v_add_u32_e32 v1, s76, v175
	ds_read_b128 v[190:193], v1
	ds_read_b128 v[194:197], v1 offset:1024
	ds_read_b128 v[198:201], v1 offset:2048
	ds_read_b128 v[202:205], v1 offset:3072
	s_add_u32 s58, s58, 0x80000
	s_addc_u32 s59, s59, 0
	s_mov_b32 m0, s65
	v_lshl_add_u64 v[6:7], s[58:59], 0, v[156:157]
	ds_read_b128 v[206:209], v179 offset:32768
	ds_read_b128 v[214:217], v179 offset:33792
	ds_read_b128 v[218:221], v179 offset:34816
	ds_read_b128 v[222:225], v179 offset:35840
	ds_read_b128 v[226:229], v179 offset:36864
	ds_read_b128 v[230:233], v179 offset:37888
	ds_read_b128 v[234:237], v179 offset:38912
	ds_read_b128 v[238:241], v179 offset:39936
	global_load_lds_dwordx4 v[6:7], off
	s_mov_b32 m0, s66
	v_lshl_add_u64 v[6:7], s[58:59], 0, v[160:161]
	global_load_lds_dwordx4 v[6:7], off
	s_waitcnt vmcnt(8) lgkmcnt(0)
	s_setprio 0
	s_barrier
	v_mfma_f32_16x16x32_bf16 v[128:131], v[140:143], v[206:209], v[128:131]
	v_mfma_f32_16x16x32_bf16 v[128:131], v[144:147], v[214:217], v[128:131]
	v_mfma_f32_16x16x32_bf16 v[124:127], v[148:151], v[206:209], v[124:127]
	v_mfma_f32_16x16x32_bf16 v[124:127], v[152:155], v[214:217], v[124:127]
	v_mfma_f32_16x16x32_bf16 v[112:115], v[140:143], v[218:221], v[112:115]
	v_mfma_f32_16x16x32_bf16 v[112:115], v[144:147], v[222:225], v[112:115]
	v_mfma_f32_16x16x32_bf16 v[108:111], v[148:151], v[218:221], v[108:111]
	v_mfma_f32_16x16x32_bf16 v[108:111], v[152:155], v[222:225], v[108:111]
	v_mfma_f32_16x16x32_bf16 v[96:99], v[140:143], v[226:229], v[96:99]
	v_mfma_f32_16x16x32_bf16 v[96:99], v[144:147], v[230:233], v[96:99]
	v_mfma_f32_16x16x32_bf16 v[92:95], v[148:151], v[226:229], v[92:95]
	v_mfma_f32_16x16x32_bf16 v[92:95], v[152:155], v[230:233], v[92:95]
	v_mfma_f32_16x16x32_bf16 v[80:83], v[140:143], v[234:237], v[80:83]
	v_mfma_f32_16x16x32_bf16 v[80:83], v[144:147], v[238:241], v[80:83]
	v_mfma_f32_16x16x32_bf16 v[76:79], v[148:151], v[234:237], v[76:79]
	v_mfma_f32_16x16x32_bf16 v[76:79], v[152:155], v[238:241], v[76:79]
	v_mfma_f32_16x16x32_bf16 v[120:123], v[190:193], v[206:209], v[120:123]
	v_mfma_f32_16x16x32_bf16 v[120:123], v[194:197], v[214:217], v[120:123]
	v_mfma_f32_16x16x32_bf16 v[116:119], v[198:201], v[206:209], v[116:119]
	v_mfma_f32_16x16x32_bf16 v[116:119], v[202:205], v[214:217], v[116:119]
	v_mfma_f32_16x16x32_bf16 v[104:107], v[190:193], v[218:221], v[104:107]
	v_mfma_f32_16x16x32_bf16 v[104:107], v[194:197], v[222:225], v[104:107]
	v_mfma_f32_16x16x32_bf16 v[100:103], v[198:201], v[218:221], v[100:103]
	v_mfma_f32_16x16x32_bf16 v[100:103], v[202:205], v[222:225], v[100:103]
	v_mfma_f32_16x16x32_bf16 v[88:91], v[190:193], v[226:229], v[88:91]
	v_mfma_f32_16x16x32_bf16 v[88:91], v[194:197], v[230:233], v[88:91]
	v_mfma_f32_16x16x32_bf16 v[84:87], v[198:201], v[226:229], v[84:87]
	v_mfma_f32_16x16x32_bf16 v[84:87], v[202:205], v[230:233], v[84:87]
	v_mfma_f32_16x16x32_bf16 v[72:75], v[190:193], v[234:237], v[72:75]
	v_mfma_f32_16x16x32_bf16 v[72:75], v[194:197], v[238:241], v[72:75]
	v_mfma_f32_16x16x32_bf16 v[68:71], v[198:201], v[234:237], v[68:71]
	v_mfma_f32_16x16x32_bf16 v[68:71], v[202:205], v[238:241], v[68:71]
	s_barrier
; #define PG8_STAGE(bufoff, gbase, voff) do { _Pragma("unroll") for (int _i = 0; _i < 2; ++_i) \
;         __builtin_amdgcn_global_load_lds((const unsigned*)((const char*)(gbase) + (voff)[_i]), (PG8_LAS unsigned*)(lds + (bufoff) + ldsw + _i * 8192), 16, 0, 0); } while (0)
; #define PG8_WAIT_V(n) asm volatile("s_waitcnt vmcnt(" #n ")" ::: "memory")
; #define PG8_WAIT_L(n) asm volatile("s_waitcnt lgkmcnt(" #n ")" ::: "memory")
; #define PG8_BAR __builtin_amdgcn_s_barrier()
; #define PG8_SCHED __builtin_amdgcn_sched_barrier(0)
;     ...
;             PG8_LDA(At, 1, 1); PG8_STAGE(PG8_SB(1, 0), b3, voffB); PG8_STAGE(PG8_SB(1, 1), b3 + hstep, voffB); PG8_STAGE(PG8_SA(1, 0), a3, voffA);
;             PG8_WAIT_V(8); PG8_WAIT_L(0); PG8_BAR; PG8_MMA(1, 0, At, B0); PG8_MMA(1, 1, At, B1); PG8_BAR; PG8_SCHED;
	s_setprio 1
	s_add_i32 s33, s33, s62
	v_lshl_add_u64 v[6:7], v[210:211], 0, s[40:41]
	s_mov_b32 m0, s33
	ds_read_b128 v[206:209], v179 offset:49152
	ds_read_b128 v[214:217], v179 offset:50176
	ds_read_b128 v[218:221], v179 offset:51200
	ds_read_b128 v[222:225], v179 offset:52224
	ds_read_b128 v[226:229], v179 offset:53248
	ds_read_b128 v[230:233], v179 offset:54272
	ds_read_b128 v[234:237], v179 offset:55296
	ds_read_b128 v[238:241], v179 offset:56320
	global_load_lds_dwordx4 v[6:7], off
	s_add_i32 m0, s33, 0x2000
	s_add_u32 s56, s56, 0x80080
	v_lshl_add_u64 v[6:7], v[242:243], 0, s[40:41]
	s_addc_u32 s57, s57, 0
	s_add_i32 s33, s76, s62
	global_load_lds_dwordx4 v[6:7], off
	s_mov_b32 m0, s33
	v_lshl_add_u64 v[6:7], s[56:57], 0, v[158:159]
	global_load_lds_dwordx4 v[6:7], off
	s_add_i32 m0, s33, 0x2000
	v_lshl_add_u64 v[6:7], s[56:57], 0, v[162:163]
	global_load_lds_dwordx4 v[6:7], off
	s_mov_b32 m0, s68
	v_lshl_add_u64 v[6:7], v[244:245], 0, s[40:41]
	global_load_lds_dwordx4 v[6:7], off
	s_mov_b32 m0, s69
	v_lshl_add_u64 v[6:7], v[246:247], 0, s[40:41]
	global_load_lds_dwordx4 v[6:7], off
	s_waitcnt vmcnt(8) lgkmcnt(0)
	s_setprio 0
	s_barrier
	v_mfma_f32_16x16x32_bf16 v[64:67], v[140:143], v[206:209], v[64:67]
	v_mfma_f32_16x16x32_bf16 v[64:67], v[144:147], v[214:217], v[64:67]
	v_mfma_f32_16x16x32_bf16 v[60:63], v[148:151], v[206:209], v[60:63]
	v_mfma_f32_16x16x32_bf16 v[60:63], v[152:155], v[214:217], v[60:63]
	v_mfma_f32_16x16x32_bf16 v[48:51], v[140:143], v[218:221], v[48:51]
	v_mfma_f32_16x16x32_bf16 v[48:51], v[144:147], v[222:225], v[48:51]
	v_mfma_f32_16x16x32_bf16 v[44:47], v[148:151], v[218:221], v[44:47]
	v_mfma_f32_16x16x32_bf16 v[44:47], v[152:155], v[222:225], v[44:47]
	v_mfma_f32_16x16x32_bf16 v[32:35], v[140:143], v[226:229], v[32:35]
	v_mfma_f32_16x16x32_bf16 v[32:35], v[144:147], v[230:233], v[32:35]
	v_mfma_f32_16x16x32_bf16 v[28:31], v[148:151], v[226:229], v[28:31]
	v_mfma_f32_16x16x32_bf16 v[28:31], v[152:155], v[230:233], v[28:31]
	v_mfma_f32_16x16x32_bf16 v[16:19], v[140:143], v[234:237], v[16:19]
	v_mfma_f32_16x16x32_bf16 v[16:19], v[144:147], v[238:241], v[16:19]
	v_mfma_f32_16x16x32_bf16 v[12:15], v[148:151], v[234:237], v[12:15]
	v_mfma_f32_16x16x32_bf16 v[12:15], v[152:155], v[238:241], v[12:15]
	v_mfma_f32_16x16x32_bf16 v[56:59], v[190:193], v[206:209], v[56:59]
	v_mfma_f32_16x16x32_bf16 v[52:55], v[198:201], v[206:209], v[52:55]
	v_mfma_f32_16x16x32_bf16 v[40:43], v[190:193], v[218:221], v[40:43]
	v_mfma_f32_16x16x32_bf16 v[36:39], v[198:201], v[218:221], v[36:39]
	v_mfma_f32_16x16x32_bf16 v[24:27], v[190:193], v[226:229], v[24:27]
	v_mfma_f32_16x16x32_bf16 v[20:23], v[198:201], v[226:229], v[20:23]
	v_mfma_f32_16x16x32_bf16 v[6:9], v[190:193], v[234:237], v[8:11]
	v_mfma_f32_16x16x32_bf16 v[2:5], v[198:201], v[234:237], v[2:5]
	v_mfma_f32_16x16x32_bf16 v[56:59], v[194:197], v[214:217], v[56:59]
	v_mfma_f32_16x16x32_bf16 v[52:55], v[202:205], v[214:217], v[52:55]
	v_mfma_f32_16x16x32_bf16 v[40:43], v[194:197], v[222:225], v[40:43]
	v_mfma_f32_16x16x32_bf16 v[36:39], v[202:205], v[222:225], v[36:39]
	v_mfma_f32_16x16x32_bf16 v[24:27], v[194:197], v[230:233], v[24:27]
	v_mfma_f32_16x16x32_bf16 v[20:23], v[202:205], v[230:233], v[20:23]
	v_mfma_f32_16x16x32_bf16 v[8:11], v[194:197], v[238:241], v[6:9]
	v_mfma_f32_16x16x32_bf16 v[4:7], v[202:205], v[238:241], v[2:5]
	s_barrier
	s_setprio 1
	s_add_i32 s75, s75, 2
	s_add_u32 s54, s54, 0x100
	s_addc_u32 s55, s55, 0
	s_cmp_gt_u32 s75, 29
	s_cbranch_scc1 .LBB0_671

; #define PG8_STAGE(bufoff, gbase, voff) do { _Pragma("unroll") for (int _i = 0; _i < 2; ++_i) \
;         __builtin_amdgcn_global_load_lds((const unsigned*)((const char*)(gbase) + (voff)[_i]), (PG8_LAS unsigned*)(lds + (bufoff) + ldsw + _i * 8192), 16, 0, 0); } while (0)
; #define PG8_WAIT_V(n) asm volatile("s_waitcnt vmcnt(" #n ")" ::: "memory")
; #define PG8_WAIT_L(n) asm volatile("s_waitcnt lgkmcnt(" #n ")" ::: "memory")
; #define PG8_BAR __builtin_amdgcn_s_barrier()
; #define PG8_SCHED __builtin_amdgcn_sched_barrier(0)
;     ...
;             const bool last = (t == nt - 2);
;             const char* a1 = cA + (size_t)(t + 1) * kstep;
;             const char* a2 = last ? nA : cA + (size_t)(t + 2) * kstep; const char* b2 = last ? nB : cB + (size_t)(t + 2) * kstep;
;             const char* a3 = a2 + kstep; const char* b3 = b2 + kstep;
;             if (last && has_next) S.a_ready(nxt);
;             if (last) E.pre(pre, cur, wr, fr);
;             if constexpr (MIDK > 0) { if (t == MIDK / BK) E.mid(acc, cur, wr, wc, fr, fq); }
;             if constexpr (SP2) {
;             PG8_LDB(B0, 0, 0); PG8_LDB(B1, 0, 1); PG8_SCHED; PG8_LDA(At, 0, 0); PG8_STAGE(PG8_SA(1, 1), a1 + hstep, voffA);
;             PG8_WAIT_V(8); PG8_WAIT_L(0); PG8_BAR; PG8_MMA(0, 0, At, B0); PG8_MMA(0, 1, At, B1); PG8_BAR; PG8_SCHED;
;             PG8_LDA(At, 0, 1); PG8_STAGE(PG8_SB(0, 0), b2, voffB); PG8_STAGE(PG8_SB(0, 1), b2 + hstep, voffB); PG8_STAGE(PG8_SA(0, 0), a2, voffA);
;             PG8_WAIT_V(8); PG8_WAIT_L(0); PG8_BAR; PG8_MMA(1, 0, At, B0); PG8_MMA(1, 1, At, B1); PG8_BAR; PG8_SCHED;
.LBB0_851:
	v_add_u32_e32 v157, s60, v149
	ds_read_b128 v[166:169], v157
	ds_read_b128 v[170:173], v157 offset:1024
	ds_read_b128 v[174:177], v157 offset:2048
	ds_read_b128 v[178:181], v157 offset:3072
	v_add_u32_e32 v157, s61, v149
	ds_read_b128 v[182:185], v157
	ds_read_b128 v[186:189], v157 offset:1024
	ds_read_b128 v[190:193], v157 offset:2048
	ds_read_b128 v[194:197], v157 offset:3072
	s_add_u32 s33, s42, 0xfffc0080
	s_addc_u32 s46, s43, -1
	s_and_b64 s[44:45], s[44:45], exec
	s_cselect_b32 s47, s34, s46
	s_cselect_b32 s46, s35, s33
	s_cselect_b32 s45, s25, s66
	s_cselect_b32 s44, s37, s65
	v_lshl_add_u64 v[210:211], s[42:43], 0, v[138:139]
	s_add_i32 m0, s51, 0xc000
	ds_read_b128 v[198:201], v153
	ds_read_b128 v[202:205], v153 offset:1024
	ds_read_b128 v[206:209], v153 offset:2048
	ds_read_b128 v[214:217], v153 offset:3072
	ds_read_b128 v[218:221], v153 offset:4096
	ds_read_b128 v[222:225], v153 offset:5120
	ds_read_b128 v[226:229], v153 offset:6144
	ds_read_b128 v[230:233], v153 offset:7168
	global_load_lds_dwordx4 v[210:211], off
	s_add_i32 m0, s51, 0xe000
	v_lshl_add_u64 v[210:211], s[42:43], 0, v[140:141]
	global_load_lds_dwordx4 v[210:211], off
	s_waitcnt vmcnt(8) lgkmcnt(0)
	s_setprio 0
	s_barrier
	v_mfma_i32_16x16x64_i8 v[124:127], v[166:169], v[198:201], v[124:127]
	v_mfma_i32_16x16x64_i8 v[124:127], v[170:173], v[202:205], v[124:127]
	v_mfma_i32_16x16x64_i8 v[120:123], v[174:177], v[198:201], v[120:123]
	v_mfma_i32_16x16x64_i8 v[120:123], v[178:181], v[202:205], v[120:123]
	v_mfma_i32_16x16x64_i8 v[108:111], v[166:169], v[206:209], v[108:111]
	v_mfma_i32_16x16x64_i8 v[108:111], v[170:173], v[214:217], v[108:111]
	v_mfma_i32_16x16x64_i8 v[100:103], v[174:177], v[206:209], v[100:103]
	v_mfma_i32_16x16x64_i8 v[100:103], v[178:181], v[214:217], v[100:103]
	v_mfma_i32_16x16x64_i8 v[92:95], v[166:169], v[218:221], v[92:95]
	v_mfma_i32_16x16x64_i8 v[92:95], v[170:173], v[222:225], v[92:95]
	v_mfma_i32_16x16x64_i8 v[84:87], v[174:177], v[218:221], v[84:87]
	v_mfma_i32_16x16x64_i8 v[84:87], v[178:181], v[222:225], v[84:87]
	v_mfma_i32_16x16x64_i8 v[76:79], v[166:169], v[226:229], v[76:79]
	v_mfma_i32_16x16x64_i8 v[76:79], v[170:173], v[230:233], v[76:79]
	v_mfma_i32_16x16x64_i8 v[68:71], v[174:177], v[226:229], v[68:71]
	v_mfma_i32_16x16x64_i8 v[68:71], v[178:181], v[230:233], v[68:71]
	v_mfma_i32_16x16x64_i8 v[116:119], v[182:185], v[198:201], v[116:119]
	v_mfma_i32_16x16x64_i8 v[116:119], v[186:189], v[202:205], v[116:119]
	v_mfma_i32_16x16x64_i8 v[112:115], v[190:193], v[198:201], v[112:115]
	v_mfma_i32_16x16x64_i8 v[112:115], v[194:197], v[202:205], v[112:115]
	v_mfma_i32_16x16x64_i8 v[104:107], v[182:185], v[206:209], v[104:107]
	v_mfma_i32_16x16x64_i8 v[104:107], v[186:189], v[214:217], v[104:107]
	v_mfma_i32_16x16x64_i8 v[96:99], v[190:193], v[206:209], v[96:99]
	v_mfma_i32_16x16x64_i8 v[96:99], v[194:197], v[214:217], v[96:99]
	v_mfma_i32_16x16x64_i8 v[88:91], v[182:185], v[218:221], v[88:91]
	v_mfma_i32_16x16x64_i8 v[88:91], v[186:189], v[222:225], v[88:91]
	v_mfma_i32_16x16x64_i8 v[80:83], v[190:193], v[218:221], v[80:83]
	v_mfma_i32_16x16x64_i8 v[80:83], v[194:197], v[222:225], v[80:83]
	v_mfma_i32_16x16x64_i8 v[72:75], v[182:185], v[226:229], v[72:75]
	v_mfma_i32_16x16x64_i8 v[72:75], v[186:189], v[230:233], v[72:75]
	v_mfma_i32_16x16x64_i8 v[64:67], v[190:193], v[226:229], v[64:67]
	v_mfma_i32_16x16x64_i8 v[64:67], v[194:197], v[230:233], v[64:67]
	s_barrier
	s_setprio 1
	s_add_i32 s33, s60, s48
	v_lshl_add_u64 v[210:211], s[44:45], 0, v[132:133]
	s_mov_b32 m0, s33
	ds_read_b128 v[198:201], v153 offset:16384
	ds_read_b128 v[202:205], v153 offset:17408
	ds_read_b128 v[206:209], v153 offset:18432
	ds_read_b128 v[214:217], v153 offset:19456
	ds_read_b128 v[218:221], v153 offset:20480
	ds_read_b128 v[222:225], v153 offset:21504
	ds_read_b128 v[226:229], v153 offset:22528
	ds_read_b128 v[230:233], v153 offset:23552
	global_load_lds_dwordx4 v[210:211], off
	s_add_i32 m0, s33, 0x2000
	s_add_u32 s68, s44, 0x40000
	v_lshl_add_u64 v[234:235], s[44:45], 0, v[128:129]
	s_addc_u32 s69, s45, 0
	s_add_i32 s33, s61, s48
	global_load_lds_dwordx4 v[234:235], off
	v_lshl_add_u64 v[236:237], s[68:69], 0, v[132:133]
	s_mov_b32 m0, s33
	v_lshl_add_u64 v[238:239], s[46:47], 0, v[130:131]
	global_load_lds_dwordx4 v[236:237], off
	s_add_i32 m0, s33, 0x2000
	v_lshl_add_u64 v[236:237], s[68:69], 0, v[128:129]
	global_load_lds_dwordx4 v[236:237], off
	s_mov_b32 m0, s51
	v_lshl_add_u64 v[236:237], s[46:47], 0, v[134:135]
	global_load_lds_dwordx4 v[236:237], off
	s_mov_b32 m0, s52
	s_nop 0
	global_load_lds_dwordx4 v[238:239], off
	s_waitcnt vmcnt(8) lgkmcnt(0)
	s_setprio 0
	s_barrier
; #define PG8_STAGE(bufoff, gbase, voff) do { _Pragma("unroll") for (int _i = 0; _i < 2; ++_i) \
;         __builtin_amdgcn_global_load_lds((const unsigned*)((const char*)(gbase) + (voff)[_i]), (PG8_LAS unsigned*)(lds + (bufoff) + ldsw + _i * 8192), 16, 0, 0); } while (0)
; #define PG8_WAIT_V(n) asm volatile("s_waitcnt vmcnt(" #n ")" ::: "memory")
; #define PG8_WAIT_L(n) asm volatile("s_waitcnt lgkmcnt(" #n ")" ::: "memory")
; #define PG8_BAR __builtin_amdgcn_s_barrier()
; #define PG8_SCHED __builtin_amdgcn_sched_barrier(0)
;     ...
;             PG8_WAIT_V(8); PG8_WAIT_L(0); PG8_BAR; PG8_MMA(1, 0, At, B0); PG8_MMA(1, 1, At, B1); PG8_BAR; PG8_SCHED;
;             PG8_LDB(B0, 1, 0); PG8_LDB(B1, 1, 1); PG8_SCHED; PG8_LDA(At, 1, 0); PG8_STAGE(PG8_SA(0, 1), a2 + hstep, voffA);
;             PG8_WAIT_V(8); PG8_WAIT_L(0); PG8_BAR; PG8_MMA(0, 0, At, B0); PG8_MMA(0, 1, At, B1); PG8_BAR; PG8_SCHED;
	v_mfma_i32_16x16x64_i8 v[60:63], v[166:169], v[198:201], v[60:63]
	v_mfma_i32_16x16x64_i8 v[60:63], v[170:173], v[202:205], v[60:63]
	v_mfma_i32_16x16x64_i8 v[52:55], v[174:177], v[198:201], v[52:55]
	v_mfma_i32_16x16x64_i8 v[52:55], v[178:181], v[202:205], v[52:55]
	v_mfma_i32_16x16x64_i8 v[44:47], v[166:169], v[206:209], v[44:47]
	v_mfma_i32_16x16x64_i8 v[44:47], v[170:173], v[214:217], v[44:47]
	v_mfma_i32_16x16x64_i8 v[36:39], v[174:177], v[206:209], v[36:39]
	v_mfma_i32_16x16x64_i8 v[36:39], v[178:181], v[214:217], v[36:39]
	v_mfma_i32_16x16x64_i8 v[28:31], v[166:169], v[218:221], v[28:31]
	v_mfma_i32_16x16x64_i8 v[28:31], v[170:173], v[222:225], v[28:31]
	v_mfma_i32_16x16x64_i8 v[20:23], v[174:177], v[218:221], v[20:23]
	v_mfma_i32_16x16x64_i8 v[20:23], v[178:181], v[222:225], v[20:23]
	v_mfma_i32_16x16x64_i8 v[12:15], v[166:169], v[226:229], v[12:15]
	v_mfma_i32_16x16x64_i8 v[12:15], v[170:173], v[230:233], v[12:15]
	v_mfma_i32_16x16x64_i8 v[4:7], v[174:177], v[226:229], v[4:7]
	v_mfma_i32_16x16x64_i8 v[4:7], v[178:181], v[230:233], v[4:7]
	v_mfma_i32_16x16x64_i8 v[56:59], v[182:185], v[198:201], v[56:59]
	v_mfma_i32_16x16x64_i8 v[56:59], v[186:189], v[202:205], v[56:59]
	v_mfma_i32_16x16x64_i8 v[48:51], v[190:193], v[198:201], v[48:51]
	v_mfma_i32_16x16x64_i8 v[48:51], v[194:197], v[202:205], v[48:51]
	v_mfma_i32_16x16x64_i8 v[40:43], v[182:185], v[206:209], v[40:43]
	v_mfma_i32_16x16x64_i8 v[40:43], v[186:189], v[214:217], v[40:43]
	v_mfma_i32_16x16x64_i8 v[32:35], v[190:193], v[206:209], v[32:35]
	v_mfma_i32_16x16x64_i8 v[32:35], v[194:197], v[214:217], v[32:35]
	v_mfma_i32_16x16x64_i8 v[24:27], v[182:185], v[218:221], v[24:27]
	v_mfma_i32_16x16x64_i8 v[24:27], v[186:189], v[222:225], v[24:27]
	v_mfma_i32_16x16x64_i8 v[16:19], v[190:193], v[218:221], v[16:19]
	v_mfma_i32_16x16x64_i8 v[16:19], v[194:197], v[222:225], v[16:19]
	v_mfma_i32_16x16x64_i8 v[8:11], v[182:185], v[226:229], v[8:11]
	v_mfma_i32_16x16x64_i8 v[8:11], v[186:189], v[230:233], v[8:11]
	v_mfma_i32_16x16x64_i8 v[0:3], v[190:193], v[226:229], v[0:3]
	v_mfma_i32_16x16x64_i8 v[0:3], v[194:197], v[230:233], v[0:3]
	s_barrier
	s_setprio 1
	s_add_i32 s33, 0, 0x18000
	v_add_u32_e32 v157, s33, v149
	s_add_i32 s68, 0, 0x1c000
	ds_read_b128 v[166:169], v157
	ds_read_b128 v[170:173], v157 offset:1024
	ds_read_b128 v[174:177], v157 offset:2048
	ds_read_b128 v[178:181], v157 offset:3072
	v_add_u32_e32 v157, s68, v149
	ds_read_b128 v[182:185], v157
	ds_read_b128 v[186:189], v157 offset:1024
	ds_read_b128 v[190:193], v157 offset:2048
	ds_read_b128 v[194:197], v157 offset:3072
	s_add_u32 s46, s46, 0x40000
	s_addc_u32 s47, s47, 0
	s_mov_b32 m0, s53
	v_lshl_add_u64 v[240:241], s[46:47], 0, v[134:135]
	ds_read_b128 v[198:201], v153 offset:32768
	ds_read_b128 v[202:205], v153 offset:33792
	ds_read_b128 v[206:209], v153 offset:34816
	ds_read_b128 v[214:217], v153 offset:35840
	ds_read_b128 v[218:221], v153 offset:36864
	ds_read_b128 v[222:225], v153 offset:37888
	ds_read_b128 v[226:229], v153 offset:38912
	ds_read_b128 v[230:233], v153 offset:39936
	global_load_lds_dwordx4 v[240:241], off
	s_mov_b32 m0, s54
	v_lshl_add_u64 v[240:241], s[46:47], 0, v[130:131]
	global_load_lds_dwordx4 v[240:241], off
	s_waitcnt vmcnt(8) lgkmcnt(0)
	s_setprio 0
	s_barrier
	v_mfma_i32_16x16x64_i8 v[124:127], v[166:169], v[198:201], v[124:127]
	v_mfma_i32_16x16x64_i8 v[124:127], v[170:173], v[202:205], v[124:127]
	v_mfma_i32_16x16x64_i8 v[120:123], v[174:177], v[198:201], v[120:123]
	v_mfma_i32_16x16x64_i8 v[120:123], v[178:181], v[202:205], v[120:123]
	v_mfma_i32_16x16x64_i8 v[108:111], v[166:169], v[206:209], v[108:111]
	v_mfma_i32_16x16x64_i8 v[108:111], v[170:173], v[214:217], v[108:111]
	v_mfma_i32_16x16x64_i8 v[100:103], v[174:177], v[206:209], v[100:103]
	v_mfma_i32_16x16x64_i8 v[100:103], v[178:181], v[214:217], v[100:103]
	v_mfma_i32_16x16x64_i8 v[92:95], v[166:169], v[218:221], v[92:95]
	v_mfma_i32_16x16x64_i8 v[92:95], v[170:173], v[222:225], v[92:95]
	v_mfma_i32_16x16x64_i8 v[84:87], v[174:177], v[218:221], v[84:87]
	v_mfma_i32_16x16x64_i8 v[84:87], v[178:181], v[222:225], v[84:87]
	v_mfma_i32_16x16x64_i8 v[76:79], v[166:169], v[226:229], v[76:79]
	v_mfma_i32_16x16x64_i8 v[76:79], v[170:173], v[230:233], v[76:79]
	v_mfma_i32_16x16x64_i8 v[68:71], v[174:177], v[226:229], v[68:71]
	v_mfma_i32_16x16x64_i8 v[68:71], v[178:181], v[230:233], v[68:71]
	v_mfma_i32_16x16x64_i8 v[116:119], v[182:185], v[198:201], v[116:119]
	v_mfma_i32_16x16x64_i8 v[116:119], v[186:189], v[202:205], v[116:119]
	v_mfma_i32_16x16x64_i8 v[112:115], v[190:193], v[198:201], v[112:115]
	v_mfma_i32_16x16x64_i8 v[112:115], v[194:197], v[202:205], v[112:115]
	v_mfma_i32_16x16x64_i8 v[104:107], v[182:185], v[206:209], v[104:107]
	v_mfma_i32_16x16x64_i8 v[104:107], v[186:189], v[214:217], v[104:107]
	v_mfma_i32_16x16x64_i8 v[96:99], v[190:193], v[206:209], v[96:99]
	v_mfma_i32_16x16x64_i8 v[96:99], v[194:197], v[214:217], v[96:99]
	v_mfma_i32_16x16x64_i8 v[88:91], v[182:185], v[218:221], v[88:91]
	v_mfma_i32_16x16x64_i8 v[88:91], v[186:189], v[222:225], v[88:91]
	v_mfma_i32_16x16x64_i8 v[80:83], v[190:193], v[218:221], v[80:83]
	v_mfma_i32_16x16x64_i8 v[80:83], v[194:197], v[222:225], v[80:83]
	v_mfma_i32_16x16x64_i8 v[72:75], v[182:185], v[226:229], v[72:75]
	v_mfma_i32_16x16x64_i8 v[72:75], v[186:189], v[230:233], v[72:75]
	v_mfma_i32_16x16x64_i8 v[64:67], v[190:193], v[226:229], v[64:67]
	v_mfma_i32_16x16x64_i8 v[64:67], v[194:197], v[230:233], v[64:67]
	s_barrier
; #define PG8_STAGE(bufoff, gbase, voff) do { _Pragma("unroll") for (int _i = 0; _i < 2; ++_i) \
;         __builtin_amdgcn_global_load_lds((const unsigned*)((const char*)(gbase) + (voff)[_i]), (PG8_LAS unsigned*)(lds + (bufoff) + ldsw + _i * 8192), 16, 0, 0); } while (0)
; #define PG8_WAIT_V(n) asm volatile("s_waitcnt vmcnt(" #n ")" ::: "memory")
; #define PG8_WAIT_L(n) asm volatile("s_waitcnt lgkmcnt(" #n ")" ::: "memory")
; #define PG8_BAR __builtin_amdgcn_s_barrier()
; #define PG8_SCHED __builtin_amdgcn_sched_barrier(0)
;     ...
;             PG8_LDA(At, 1, 1); PG8_STAGE(PG8_SB(1, 0), b3, voffB); PG8_STAGE(PG8_SB(1, 1), b3 + hstep, voffB); PG8_STAGE(PG8_SA(1, 0), a3, voffA);
;             PG8_WAIT_V(8); PG8_WAIT_L(0); PG8_BAR; PG8_MMA(1, 0, At, B0); PG8_MMA(1, 1, At, B1); PG8_BAR; PG8_SCHED;
	s_setprio 1
	s_add_i32 s33, s33, s48
	v_lshl_add_u64 v[210:211], v[210:211], 0, s[10:11]
	s_mov_b32 m0, s33
	ds_read_b128 v[198:201], v153 offset:49152
	ds_read_b128 v[202:205], v153 offset:50176
	ds_read_b128 v[206:209], v153 offset:51200
	ds_read_b128 v[214:217], v153 offset:52224
	ds_read_b128 v[218:221], v153 offset:53248
	ds_read_b128 v[222:225], v153 offset:54272
	ds_read_b128 v[226:229], v153 offset:55296
	ds_read_b128 v[230:233], v153 offset:56320
	global_load_lds_dwordx4 v[210:211], off
	s_add_i32 m0, s33, 0x2000
	s_add_u32 s44, s44, 0x40080
	v_lshl_add_u64 v[210:211], v[234:235], 0, s[10:11]
	s_addc_u32 s45, s45, 0
	s_add_i32 s33, s68, s48
	global_load_lds_dwordx4 v[210:211], off
	s_mov_b32 m0, s33
	v_lshl_add_u64 v[210:211], s[44:45], 0, v[132:133]
	global_load_lds_dwordx4 v[210:211], off
	s_add_i32 m0, s33, 0x2000
	v_lshl_add_u64 v[210:211], s[44:45], 0, v[128:129]
	global_load_lds_dwordx4 v[210:211], off
	s_mov_b32 m0, s56
	v_lshl_add_u64 v[210:211], v[236:237], 0, s[10:11]
	global_load_lds_dwordx4 v[210:211], off
	s_mov_b32 m0, s57
	v_lshl_add_u64 v[210:211], v[238:239], 0, s[10:11]
	global_load_lds_dwordx4 v[210:211], off
	s_waitcnt vmcnt(8) lgkmcnt(0)
	s_setprio 0
	s_barrier
	v_mfma_i32_16x16x64_i8 v[60:63], v[166:169], v[198:201], v[60:63]
	v_mfma_i32_16x16x64_i8 v[60:63], v[170:173], v[202:205], v[60:63]
	v_mfma_i32_16x16x64_i8 v[52:55], v[174:177], v[198:201], v[52:55]
	v_mfma_i32_16x16x64_i8 v[52:55], v[178:181], v[202:205], v[52:55]
	v_mfma_i32_16x16x64_i8 v[44:47], v[166:169], v[206:209], v[44:47]
	v_mfma_i32_16x16x64_i8 v[44:47], v[170:173], v[214:217], v[44:47]
	v_mfma_i32_16x16x64_i8 v[36:39], v[174:177], v[206:209], v[36:39]
	v_mfma_i32_16x16x64_i8 v[36:39], v[178:181], v[214:217], v[36:39]
	v_mfma_i32_16x16x64_i8 v[28:31], v[166:169], v[218:221], v[28:31]
	v_mfma_i32_16x16x64_i8 v[28:31], v[170:173], v[222:225], v[28:31]
	v_mfma_i32_16x16x64_i8 v[20:23], v[174:177], v[218:221], v[20:23]
	v_mfma_i32_16x16x64_i8 v[20:23], v[178:181], v[222:225], v[20:23]
	v_mfma_i32_16x16x64_i8 v[12:15], v[166:169], v[226:229], v[12:15]
	v_mfma_i32_16x16x64_i8 v[12:15], v[170:173], v[230:233], v[12:15]
	v_mfma_i32_16x16x64_i8 v[4:7], v[174:177], v[226:229], v[4:7]
	v_mfma_i32_16x16x64_i8 v[4:7], v[178:181], v[230:233], v[4:7]
	v_mfma_i32_16x16x64_i8 v[56:59], v[182:185], v[198:201], v[56:59]
	v_mfma_i32_16x16x64_i8 v[56:59], v[186:189], v[202:205], v[56:59]
	v_mfma_i32_16x16x64_i8 v[48:51], v[190:193], v[198:201], v[48:51]
	v_mfma_i32_16x16x64_i8 v[48:51], v[194:197], v[202:205], v[48:51]
	v_mfma_i32_16x16x64_i8 v[40:43], v[182:185], v[206:209], v[40:43]
	v_mfma_i32_16x16x64_i8 v[40:43], v[186:189], v[214:217], v[40:43]
	v_mfma_i32_16x16x64_i8 v[32:35], v[190:193], v[206:209], v[32:35]
	v_mfma_i32_16x16x64_i8 v[32:35], v[194:197], v[214:217], v[32:35]
	v_mfma_i32_16x16x64_i8 v[24:27], v[182:185], v[218:221], v[24:27]
	v_mfma_i32_16x16x64_i8 v[24:27], v[186:189], v[222:225], v[24:27]
	v_mfma_i32_16x16x64_i8 v[16:19], v[190:193], v[218:221], v[16:19]
	v_mfma_i32_16x16x64_i8 v[16:19], v[194:197], v[222:225], v[16:19]
	v_mfma_i32_16x16x64_i8 v[8:11], v[182:185], v[226:229], v[8:11]
	v_mfma_i32_16x16x64_i8 v[8:11], v[186:189], v[230:233], v[8:11]
	v_mfma_i32_16x16x64_i8 v[0:3], v[190:193], v[226:229], v[0:3]
	v_mfma_i32_16x16x64_i8 v[0:3], v[194:197], v[230:233], v[0:3]
	s_barrier
	s_setprio 1
	s_add_i32 s67, s67, 2
	s_add_u32 s42, s42, 0x100
	s_addc_u32 s43, s43, 0
	s_add_u32 s65, s65, 0x100
	s_addc_u32 s66, s66, 0
	s_cmp_gt_u32 s67, 13
	s_cbranch_scc1 .LBB0_854

; #define PG8_STAGE(bufoff, gbase, voff) do { _Pragma("unroll") for (int _i = 0; _i < 2; ++_i) \
;         __builtin_amdgcn_global_load_lds((const unsigned*)((const char*)(gbase) + (voff)[_i]), (PG8_LAS unsigned*)(lds + (bufoff) + ldsw + _i * 8192), 16, 0, 0); } while (0)
; #define PG8_WAIT_V(n) asm volatile("s_waitcnt vmcnt(" #n ")" ::: "memory")
; #define PG8_WAIT_L(n) asm volatile("s_waitcnt lgkmcnt(" #n ")" ::: "memory")
; #define PG8_BAR __builtin_amdgcn_s_barrier()
; #define PG8_SCHED __builtin_amdgcn_sched_barrier(0)
;     ...
;             PG8_LDB(B0, 0, 0); PG8_LDB(B1, 0, 1); PG8_SCHED; PG8_LDA(At, 0, 0); PG8_STAGE(PG8_SA(1, 1), a1 + hstep, voffA);
;             PG8_WAIT_V(8); PG8_WAIT_L(0); PG8_BAR; PG8_MMA(0, 0, At, B0); PG8_MMA(0, 1, At, B1); PG8_BAR; PG8_SCHED;
;             PG8_LDA(At, 0, 1); PG8_STAGE(PG8_SB(0, 0), b2, voffB); PG8_STAGE(PG8_SB(0, 1), b2 + hstep, voffB); PG8_STAGE(PG8_SA(0, 0), a2, voffA);
;             PG8_WAIT_V(8); PG8_WAIT_L(0); PG8_BAR; PG8_MMA(1, 0, At, B0); PG8_MMA(1, 1, At, B1); PG8_BAR; PG8_SCHED;
.LBB0_936:
	ds_read_b128 v[16:19], v187
	ds_read_b128 v[20:23], v187 offset:16
	ds_read_b128 v[24:27], v187 offset:2048
	ds_read_b128 v[28:31], v187 offset:2064
	ds_read_b128 v[0:3], v188
	ds_read_b128 v[4:7], v188 offset:16
	ds_read_b128 v[8:11], v188 offset:2048
	ds_read_b128 v[12:15], v188 offset:2064
	s_add_u32 s24, s20, 0xfff50080
	s_addc_u32 s25, s21, -1
	s_cmp_eq_u32 s48, 40
	s_cselect_b32 s29, s5, s25
	s_cselect_b32 s28, s4, s24
	s_cselect_b32 s25, s19, s47
	s_cselect_b32 s24, s18, s46
	v_lshl_add_u64 v[214:215], s[20:21], 0, v[168:169]
	s_add_i32 m0, s31, 0xc000
	ds_read_b128 v[176:179], v189
	ds_read_b128 v[180:183], v189 offset:16
	ds_read_b128 v[190:193], v189 offset:2048
	ds_read_b128 v[194:197], v189 offset:2064
	ds_read_b128 v[198:201], v189 offset:4096
	ds_read_b128 v[202:205], v189 offset:4112
	ds_read_b128 v[206:209], v189 offset:6144
	ds_read_b128 v[210:213], v189 offset:6160
	global_load_lds_dwordx4 v[214:215], off
	s_add_i32 m0, s31, 0xe000
	v_lshl_add_u64 v[214:215], s[20:21], 0, v[170:171]
	global_load_lds_dwordx4 v[214:215], off
	s_waitcnt vmcnt(8) lgkmcnt(0)
	s_setprio 0
	s_barrier
	v_mfma_f32_16x16x128_f8f6f4 v[156:159], v[16:23], v[176:183], v[156:159]
	v_mfma_f32_16x16x128_f8f6f4 v[152:155], v[24:31], v[176:183], v[152:155]
	v_mfma_f32_16x16x128_f8f6f4 v[148:151], v[16:23], v[190:197], v[148:151]
	v_mfma_f32_16x16x128_f8f6f4 v[144:147], v[24:31], v[190:197], v[144:147]
	v_mfma_f32_16x16x128_f8f6f4 v[128:131], v[16:23], v[198:205], v[128:131]
	v_mfma_f32_16x16x128_f8f6f4 v[120:123], v[24:31], v[198:205], v[120:123]
	v_mfma_f32_16x16x128_f8f6f4 v[112:115], v[16:23], v[206:213], v[112:115]
	v_mfma_f32_16x16x128_f8f6f4 v[104:107], v[24:31], v[206:213], v[104:107]
	v_mfma_f32_16x16x128_f8f6f4 v[140:143], v[0:7], v[176:183], v[140:143]
	v_mfma_f32_16x16x128_f8f6f4 v[136:139], v[8:15], v[176:183], v[136:139]
	v_mfma_f32_16x16x128_f8f6f4 v[132:135], v[0:7], v[190:197], v[132:135]
	v_mfma_f32_16x16x128_f8f6f4 v[124:127], v[8:15], v[190:197], v[124:127]
	v_mfma_f32_16x16x128_f8f6f4 v[116:119], v[0:7], v[198:205], v[116:119]
	v_mfma_f32_16x16x128_f8f6f4 v[108:111], v[8:15], v[198:205], v[108:111]
	v_mfma_f32_16x16x128_f8f6f4 v[100:103], v[0:7], v[206:213], v[100:103]
	v_mfma_f32_16x16x128_f8f6f4 v[96:99], v[8:15], v[206:213], v[96:99]
	s_barrier
	s_setprio 1
	s_add_i32 s49, s40, s30
	v_lshl_add_u64 v[176:177], s[24:25], 0, v[162:163]
	s_mov_b32 m0, s49
	ds_read_b128 v[190:193], v189 offset:16384
	ds_read_b128 v[194:197], v189 offset:16400
	ds_read_b128 v[198:201], v189 offset:18432
	ds_read_b128 v[202:205], v189 offset:18448
	ds_read_b128 v[206:209], v189 offset:20480
	ds_read_b128 v[210:213], v189 offset:20496
	ds_read_b128 v[214:217], v189 offset:22528
	ds_read_b128 v[218:221], v189 offset:22544
	global_load_lds_dwordx4 v[176:177], off
	s_add_i32 m0, s49, 0x2000
	s_add_u32 s50, s24, 0xb0000
	v_lshl_add_u64 v[178:179], s[24:25], 0, v[166:167]
	s_addc_u32 s51, s25, 0
	s_add_i32 s49, s41, s30
	global_load_lds_dwordx4 v[178:179], off
	v_lshl_add_u64 v[180:181], s[50:51], 0, v[162:163]
	s_mov_b32 m0, s49
	v_lshl_add_u64 v[182:183], s[28:29], 0, v[164:165]
	global_load_lds_dwordx4 v[180:181], off
	s_add_i32 m0, s49, 0x2000
	v_lshl_add_u64 v[180:181], s[50:51], 0, v[166:167]
	global_load_lds_dwordx4 v[180:181], off
	s_mov_b32 m0, s31
	v_lshl_add_u64 v[180:181], s[28:29], 0, v[160:161]
	global_load_lds_dwordx4 v[180:181], off
	s_mov_b32 m0, s33
	s_nop 0
	global_load_lds_dwordx4 v[182:183], off
	s_waitcnt vmcnt(8) lgkmcnt(0)
	s_setprio 0
	s_barrier
	v_mfma_f32_16x16x128_f8f6f4 v[92:95], v[16:23], v[190:197], v[92:95]
	v_mfma_f32_16x16x128_f8f6f4 v[88:91], v[24:31], v[190:197], v[88:91]
	v_mfma_f32_16x16x128_f8f6f4 v[80:83], v[16:23], v[198:205], v[80:83]
	v_mfma_f32_16x16x128_f8f6f4 v[72:75], v[24:31], v[198:205], v[72:75]
	v_mfma_f32_16x16x128_f8f6f4 v[64:67], v[16:23], v[206:213], v[64:67]
	v_mfma_f32_16x16x128_f8f6f4 v[56:59], v[24:31], v[206:213], v[56:59]
	v_mfma_f32_16x16x128_f8f6f4 v[48:51], v[16:23], v[214:221], v[48:51]
	v_mfma_f32_16x16x128_f8f6f4 v[40:43], v[24:31], v[214:221], v[40:43]
	v_mfma_f32_16x16x128_f8f6f4 v[84:87], v[0:7], v[190:197], v[84:87]
	v_mfma_f32_16x16x128_f8f6f4 v[76:79], v[8:15], v[190:197], v[76:79]
	v_mfma_f32_16x16x128_f8f6f4 v[68:71], v[0:7], v[198:205], v[68:71]
	v_mfma_f32_16x16x128_f8f6f4 v[60:63], v[8:15], v[198:205], v[60:63]
	v_mfma_f32_16x16x128_f8f6f4 v[52:55], v[0:7], v[206:213], v[52:55]
	v_mfma_f32_16x16x128_f8f6f4 v[44:47], v[8:15], v[206:213], v[44:47]
	v_mfma_f32_16x16x128_f8f6f4 v[36:39], v[0:7], v[214:221], v[36:39]
	v_mfma_f32_16x16x128_f8f6f4 v[32:35], v[8:15], v[214:221], v[32:35]
	s_barrier
; #define PG8_STAGE(bufoff, gbase, voff) do { _Pragma("unroll") for (int _i = 0; _i < 2; ++_i) \
;         __builtin_amdgcn_global_load_lds((const unsigned*)((const char*)(gbase) + (voff)[_i]), (PG8_LAS unsigned*)(lds + (bufoff) + ldsw + _i * 8192), 16, 0, 0); } while (0)
; #define PG8_WAIT_V(n) asm volatile("s_waitcnt vmcnt(" #n ")" ::: "memory")
; #define PG8_WAIT_L(n) asm volatile("s_waitcnt lgkmcnt(" #n ")" ::: "memory")
; #define PG8_BAR __builtin_amdgcn_s_barrier()
; #define PG8_SCHED __builtin_amdgcn_sched_barrier(0)
;     ...
;             PG8_LDB(B0, 1, 0); PG8_LDB(B1, 1, 1); PG8_SCHED; PG8_LDA(At, 1, 0); PG8_STAGE(PG8_SA(0, 1), a2 + hstep, voffA);
;             PG8_WAIT_V(8); PG8_WAIT_L(0); PG8_BAR; PG8_MMA(0, 0, At, B0); PG8_MMA(0, 1, At, B1); PG8_BAR; PG8_SCHED;
;             PG8_LDA(At, 1, 1); PG8_STAGE(PG8_SB(1, 0), b3, voffB); PG8_STAGE(PG8_SB(1, 1), b3 + hstep, voffB); PG8_STAGE(PG8_SA(1, 0), a3, voffA);
;             PG8_WAIT_V(8); PG8_WAIT_L(0); PG8_BAR; PG8_MMA(1, 0, At, B0); PG8_MMA(1, 1, At, B1); PG8_BAR; PG8_SCHED;
;     ...
;         if constexpr (F8) asm volatile("s_nop 15\n\ts_nop 15" ::: "memory");
;         if constexpr (ALIGN_EPI) { if (wr == 0) PG8_BAR; }
	s_setprio 1
	s_add_i32 s49, 0, 0x18000
	s_add_i32 s50, 0, 0x1c000
	v_add_u32_e32 v12, s49, v185
	v_add_u32_e32 v28, s50, v185
	ds_read_b128 v[0:3], v12
	ds_read_b128 v[4:7], v12 offset:16
	ds_read_b128 v[8:11], v12 offset:2048
	ds_read_b128 v[12:15], v12 offset:2064
	ds_read_b128 v[16:19], v28
	ds_read_b128 v[20:23], v28 offset:16
	ds_read_b128 v[24:27], v28 offset:2048
	ds_read_b128 v[28:31], v28 offset:2064
	s_add_u32 s28, s28, 0xb0000
	s_addc_u32 s29, s29, 0
	s_mov_b32 m0, s34
	v_lshl_add_u64 v[222:223], s[28:29], 0, v[160:161]
	ds_read_b128 v[190:193], v189 offset:32768
	ds_read_b128 v[194:197], v189 offset:32784
	ds_read_b128 v[198:201], v189 offset:34816
	ds_read_b128 v[202:205], v189 offset:34832
	ds_read_b128 v[206:209], v189 offset:36864
	ds_read_b128 v[210:213], v189 offset:36880
	ds_read_b128 v[214:217], v189 offset:38912
	ds_read_b128 v[218:221], v189 offset:38928
	global_load_lds_dwordx4 v[222:223], off
	s_mov_b32 m0, s35
	v_lshl_add_u64 v[222:223], s[28:29], 0, v[164:165]
	global_load_lds_dwordx4 v[222:223], off
	s_waitcnt vmcnt(8) lgkmcnt(0)
	s_setprio 0
	s_barrier
	v_mfma_f32_16x16x128_f8f6f4 v[156:159], v[0:7], v[190:197], v[156:159]
	v_mfma_f32_16x16x128_f8f6f4 v[152:155], v[8:15], v[190:197], v[152:155]
	v_mfma_f32_16x16x128_f8f6f4 v[148:151], v[0:7], v[198:205], v[148:151]
	v_mfma_f32_16x16x128_f8f6f4 v[144:147], v[8:15], v[198:205], v[144:147]
	v_mfma_f32_16x16x128_f8f6f4 v[128:131], v[0:7], v[206:213], v[128:131]
	v_mfma_f32_16x16x128_f8f6f4 v[120:123], v[8:15], v[206:213], v[120:123]
	v_mfma_f32_16x16x128_f8f6f4 v[112:115], v[0:7], v[214:221], v[112:115]
	v_mfma_f32_16x16x128_f8f6f4 v[104:107], v[8:15], v[214:221], v[104:107]
	v_mfma_f32_16x16x128_f8f6f4 v[140:143], v[16:23], v[190:197], v[140:143]
	v_mfma_f32_16x16x128_f8f6f4 v[136:139], v[24:31], v[190:197], v[136:139]
	v_mfma_f32_16x16x128_f8f6f4 v[132:135], v[16:23], v[198:205], v[132:135]
	v_mfma_f32_16x16x128_f8f6f4 v[124:127], v[24:31], v[198:205], v[124:127]
	v_mfma_f32_16x16x128_f8f6f4 v[116:119], v[16:23], v[206:213], v[116:119]
	v_mfma_f32_16x16x128_f8f6f4 v[108:111], v[24:31], v[206:213], v[108:111]
	v_mfma_f32_16x16x128_f8f6f4 v[100:103], v[16:23], v[214:221], v[100:103]
	v_mfma_f32_16x16x128_f8f6f4 v[96:99], v[24:31], v[214:221], v[96:99]
	s_barrier
	s_setprio 1
	s_add_i32 s28, s49, s30
	v_lshl_add_u64 v[176:177], v[176:177], 0, s[8:9]
	s_mov_b32 m0, s28
	ds_read_b128 v[190:193], v189 offset:49152
	ds_read_b128 v[194:197], v189 offset:49168
	ds_read_b128 v[198:201], v189 offset:51200
	ds_read_b128 v[202:205], v189 offset:51216
	ds_read_b128 v[206:209], v189 offset:53248
	ds_read_b128 v[210:213], v189 offset:53264
	ds_read_b128 v[214:217], v189 offset:55296
	ds_read_b128 v[218:221], v189 offset:55312
	global_load_lds_dwordx4 v[176:177], off
	s_add_i32 m0, s28, 0x2000
	s_add_u32 s24, s24, 0xb0080
	v_lshl_add_u64 v[176:177], v[178:179], 0, s[8:9]
	s_addc_u32 s25, s25, 0
	s_add_i32 s28, s50, s30
	global_load_lds_dwordx4 v[176:177], off
	s_mov_b32 m0, s28
	v_lshl_add_u64 v[176:177], s[24:25], 0, v[162:163]
	global_load_lds_dwordx4 v[176:177], off
	s_add_i32 m0, s28, 0x2000
	v_lshl_add_u64 v[176:177], s[24:25], 0, v[166:167]
	global_load_lds_dwordx4 v[176:177], off
	s_mov_b32 m0, s37
	v_lshl_add_u64 v[176:177], v[180:181], 0, s[8:9]
	global_load_lds_dwordx4 v[176:177], off
	s_mov_b32 m0, s38
	v_lshl_add_u64 v[176:177], v[182:183], 0, s[8:9]
	global_load_lds_dwordx4 v[176:177], off
	s_waitcnt vmcnt(8) lgkmcnt(0)
	s_setprio 0
	s_barrier
	v_mfma_f32_16x16x128_f8f6f4 v[92:95], v[0:7], v[190:197], v[92:95]
	v_mfma_f32_16x16x128_f8f6f4 v[88:91], v[8:15], v[190:197], v[88:91]
	v_mfma_f32_16x16x128_f8f6f4 v[80:83], v[0:7], v[198:205], v[80:83]
	v_mfma_f32_16x16x128_f8f6f4 v[72:75], v[8:15], v[198:205], v[72:75]
	v_mfma_f32_16x16x128_f8f6f4 v[64:67], v[0:7], v[206:213], v[64:67]
	v_mfma_f32_16x16x128_f8f6f4 v[56:59], v[8:15], v[206:213], v[56:59]
	v_mfma_f32_16x16x128_f8f6f4 v[48:51], v[0:7], v[214:221], v[48:51]
	v_mfma_f32_16x16x128_f8f6f4 v[40:43], v[8:15], v[214:221], v[40:43]
	v_mfma_f32_16x16x128_f8f6f4 v[84:87], v[16:23], v[190:197], v[84:87]
	v_mfma_f32_16x16x128_f8f6f4 v[76:79], v[24:31], v[190:197], v[76:79]
	v_mfma_f32_16x16x128_f8f6f4 v[68:71], v[16:23], v[198:205], v[68:71]
	v_mfma_f32_16x16x128_f8f6f4 v[60:63], v[24:31], v[198:205], v[60:63]
	v_mfma_f32_16x16x128_f8f6f4 v[52:55], v[16:23], v[206:213], v[52:55]
	v_mfma_f32_16x16x128_f8f6f4 v[44:47], v[24:31], v[206:213], v[44:47]
	v_mfma_f32_16x16x128_f8f6f4 v[36:39], v[16:23], v[214:221], v[36:39]
	v_mfma_f32_16x16x128_f8f6f4 v[32:35], v[24:31], v[214:221], v[32:35]
	s_barrier
	s_setprio 1
	s_add_i32 s48, s48, 2
	s_add_u32 s20, s20, 0x100
	s_addc_u32 s21, s21, 0
	s_add_u32 s46, s46, 0x100
	s_addc_u32 s47, s47, 0
	s_cmp_gt_u32 s48, 41
	s_cbranch_scc0 .LBB0_936
	s_nop 15
	s_nop 15
	s_and_b64 vcc, exec, s[10:11]
	s_cbranch_vccz .LBB0_939
	s_barrier
